# attention inner loop: the 68 softmax row-sum adds moved out of the serial tail into the P.V MFMA shadows (two partial accumulators), on top of the lane-swap S5 version
# speedup vs baseline: 1.0521x; 1.0075x over previous
; DI u32x4 pack8(const float* f) { u32x4 o; o.x = pk2(f[0], f[1]); o.y = pk2(f[2], f[3]); o.z = pk2(f[4], f[5]); o.w = pk2(f[6], f[7]); return o; }
; DI float sin_rev(float r) { return __builtin_amdgcn_sinf(r); }
; DI float cos_rev(float r) { return __builtin_amdgcn_cosf(r); }
; DI void s5_phase(const KArgs& a, int zz, int o, const bf16_t* H, bf16_t* YF, bf16_t* YB, LAS unsigned char* lds, int G, int bid, int wave, int lane) {
;     ...
;         float abr, abi;
;         { const float ar = are[lane], ai = aim[lane]; const float mag = __expf(dt * ar); float rev = dt * ai * 0.15915494309189535f; rev -= floorf(rev);
;           abr = mag * cos_rev(rev); abi = mag * sin_rev(rev); }
;         bf16x8 Bb[8];
; #pragma unroll
;         for (int nt = 0; nt < 8; ++nt) {
;             const int c = 16 * nt + fr, p2 = c >> 1, part = c & 1;
;             const float ar = are[p2], ai = aim[p2]; const float mag = __expf(dt * ar); float rev = dt * ai * 0.15915494309189535f; rev -= floorf(rev);
;             const float er = mag * cos_rev(rev) - 1.f, ei = mag * sin_rev(rev); const float den = 1.f / (ar * ar + ai * ai);
;             const float cr = (er * ar + ei * ai) * den, ci = (ei * ar - er * ai) * den;
;             float v[8];
; #pragma unroll
;             for (int j = 0; j < 8; ++j) v[j] = 0.f;
;             if (fq < 2) {
; #pragma unroll
;                 for (int j = 0; j < 8; ++j) { const float br = bre[p2 * 16 + fq * 8 + j], bi = bim[p2 * 16 + fq * 8 + j]; v[j] = part ? (cr * bi + ci * br) : (cr * br - ci * bi); } }
;             Bb[nt] = __builtin_bit_cast(bf16x8, pack8(v));
;         }
;         bf16x8 Cb[4];
; #pragma unroll
;         for (int kb = 0; kb < 4; ++kb) { float v[8];
; #pragma unroll
;             for (int j = 0; j < 8; ++j) { const int p3 = kb * 16 + fq * 4 + (j >> 1); v[j] = (j & 1) ? -cim[fr * 64 + p3] : cre[fr * 64 + p3]; }
;             Cb[kb] = __builtin_bit_cast(bf16x8, pack8(v)); }
.LBB0_411:
	s_or_b64 exec, exec, s[26:27]
	s_waitcnt vmcnt(1)
	v_mul_f32_e32 v29, v29, v30
	s_waitcnt vmcnt(0)
	v_mul_f32_e32 v28, v30, v28
	v_cvt_pk_bf16_f32 v24, v24, v25
	v_cvt_pk_bf16_f32 v25, v26, v27
	v_cvt_pk_bf16_f32 v26, v31, v32
	v_mul_f32_e32 v32, 0x3fb8aa3b, v29
	v_mul_f32_e32 v29, 0.15915494, v28
	v_floor_f32_e32 v29, v29
	v_fma_f32 v28, v28, 0.15915494, -v29
	s_lshl_b64 s[0:1], s[52:53], 10
	v_cvt_pk_bf16_f32 v9, v49, v50
	v_cvt_pk_bf16_f32 v27, v33, v34
	v_cos_f32_e32 v33, v28
	v_exp_f32_e32 v49, v32
	s_lshl_b64 s[0:1], s[0:1], 2
	v_cvt_pk_bf16_f32 v8, v11, v47
	v_cvt_pk_bf16_f32 v10, v51, v52
	v_cvt_pk_bf16_f32 v11, v53, v54
	v_lshl_add_u64 v[52:53], v[120:121], 0, s[0:1]
	v_cvt_pk_bf16_f32 v16, v16, v17
	v_cvt_pk_bf16_f32 v17, v18, v19
	v_cvt_pk_bf16_f32 v18, v39, v40
	v_cvt_pk_bf16_f32 v20, v20, v21
	v_cvt_pk_bf16_f32 v21, v22, v23
	v_cvt_pk_bf16_f32 v22, v35, v36
	v_cvt_pk_bf16_f32 v23, v37, v38
	v_lshl_add_u64 v[50:51], v[118:119], 0, s[0:1]
	global_load_dwordx4 v[36:39], v[52:53], off
	v_mul_f32_e32 v122, v49, v33
	global_load_dwordx4 v[32:35], v[50:51], off
	v_cvt_pk_bf16_f32 v12, v12, v13
	v_cvt_pk_bf16_f32 v13, v14, v15
	v_cvt_pk_bf16_f32 v14, v43, v44
	v_cvt_pk_bf16_f32 v19, v41, v42
	v_cvt_pk_bf16_f32 v15, v45, v46
	v_cvt_pk_bf16_f32 v4, v48, v55
	v_sin_f32_e32 v48, v28
	s_ashr_i32 s56, s61, 4
	s_lshl_b32 s54, s56, 8
	s_lshl_b32 s52, s23, 4
	s_ashr_i32 s55, s54, 31
	v_mul_f32_e32 v125, v49, v48
	s_ashr_i32 s53, s52, 31
	v_mov_b32_e32 v49, s55
	v_or_b32_e32 v48, s54, v104
	v_lshl_add_u64 v[126:127], s[52:53], 1, v[108:109]
	v_lshlrev_b64 v[48:49], 11, v[48:49]
	v_cvt_pk_bf16_f32 v0, v63, v64
	v_cvt_pk_bf16_f32 v1, v65, v66
	v_cvt_pk_bf16_f32 v2, v67, v68
	v_cvt_pk_bf16_f32 v3, v69, v70
	v_cvt_pk_bf16_f32 v5, v56, v57
	v_cvt_pk_bf16_f32 v6, v58, v59
	v_cvt_pk_bf16_f32 v7, v60, v61
	v_cvt_pk_bf16_f32 v28, v62, v71
	v_cvt_pk_bf16_f32 v29, v72, v73
	v_cvt_pk_bf16_f32 v30, v74, v75
	v_cvt_pk_bf16_f32 v31, v76, v77
	v_lshl_add_u64 v[130:131], v[126:127], 0, v[48:49]
	s_mov_b64 s[0:1], -1
	s_andn2_b64 vcc, exec, s[8:9]
	v_xor_b32_e32 v124, 0x80000000, v125
	v_add_u32_e32 v159, 0x1800, v117
	v_add_u32_e32 v160, 0x1000, v117
	v_add_u32_e32 v161, 0x800, v117
	v_add_u32_e32 v162, 0x2e00, v158
	v_add_u32_e32 v163, 0x2c00, v158
	v_add_u32_e32 v164, 0x2a00, v158
	v_add_u32_e32 v165, 0x2800, v158
	v_add_u32_e32 v166, 0x2600, v158
	v_add_u32_e32 v167, 0x2400, v158
	v_add_u32_e32 v168, 0x2200, v158
	v_add_u32_e32 v169, 0x2000, v158
	v_lshl_add_u64 v[128:129], s[52:53], 1, v[112:113]
	s_waitcnt vmcnt(1)
	v_xor_b32_e32 v36, 0x80000000, v36
	v_xor_b32_e32 v37, 0x80000000, v37
	v_xor_b32_e32 v38, 0x80000000, v38
	v_xor_b32_e32 v39, 0x80000000, v39
	s_waitcnt vmcnt(0)
	v_cvt_pk_bf16_f32 v32, v32, v36
	v_cvt_pk_bf16_f32 v33, v33, v37
	v_cvt_pk_bf16_f32 v34, v34, v38
	v_cvt_pk_bf16_f32 v35, v35, v39
	global_load_dwordx4 v[36:39], v[50:51], off offset:64
	global_load_dwordx4 v[40:43], v[52:53], off offset:64
	s_waitcnt vmcnt(0)
	v_xor_b32_e32 v40, 0x80000000, v40
	v_xor_b32_e32 v41, 0x80000000, v41
	v_xor_b32_e32 v42, 0x80000000, v42
	v_xor_b32_e32 v43, 0x80000000, v43
	v_cvt_pk_bf16_f32 v36, v36, v40
	v_cvt_pk_bf16_f32 v37, v37, v41
	v_cvt_pk_bf16_f32 v38, v38, v42
	v_cvt_pk_bf16_f32 v39, v39, v43
	global_load_dwordx4 v[40:43], v[50:51], off offset:128
	global_load_dwordx4 v[44:47], v[52:53], off offset:128
	s_waitcnt vmcnt(0)
	v_xor_b32_e32 v44, 0x80000000, v44
	v_xor_b32_e32 v45, 0x80000000, v45
	v_xor_b32_e32 v46, 0x80000000, v46
	v_xor_b32_e32 v47, 0x80000000, v47
	v_cvt_pk_bf16_f32 v40, v40, v44
	v_cvt_pk_bf16_f32 v41, v41, v45
	v_cvt_pk_bf16_f32 v42, v42, v46
	v_cvt_pk_bf16_f32 v43, v43, v47
	global_load_dwordx4 v[44:47], v[50:51], off offset:192
	s_nop 0
	global_load_dwordx4 v[50:53], v[52:53], off offset:192
	s_waitcnt vmcnt(0)
	v_xor_b32_e32 v50, 0x80000000, v50
	v_xor_b32_e32 v51, 0x80000000, v51
	v_xor_b32_e32 v52, 0x80000000, v52
	v_xor_b32_e32 v53, 0x80000000, v53
	v_cvt_pk_bf16_f32 v44, v44, v50
	v_cvt_pk_bf16_f32 v45, v45, v51
	v_cvt_pk_bf16_f32 v46, v46, v52
	v_cvt_pk_bf16_f32 v47, v47, v53
	v_and_b32_e32 v244, 7, v152
	v_lshlrev_b32_e32 v244, 1, v244
	v_and_b32_e32 v245, 48, v152
	v_add_u32_e32 v244, v244, v245
	v_lshlrev_b32_e32 v244, 2, v244
	v_add_u32_e32 v245, 4, v244
	v_and_b32_e32 v246, 8, v152
	v_cmp_ne_u32_e64 s[98:99], 0, v246
	ds_bpermute_b32 v247, v244, v24
	ds_bpermute_b32 v248, v244, v20
	s_waitcnt lgkmcnt(0)
	v_cndmask_b32_e64 v178, v247, v248, s[98:99]
	ds_bpermute_b32 v247, v244, v25
	ds_bpermute_b32 v248, v244, v21
	s_waitcnt lgkmcnt(0)
	v_cndmask_b32_e64 v179, v247, v248, s[98:99]
	ds_bpermute_b32 v247, v244, v26
	ds_bpermute_b32 v248, v244, v22
	s_waitcnt lgkmcnt(0)
	v_cndmask_b32_e64 v180, v247, v248, s[98:99]
	ds_bpermute_b32 v247, v244, v27
	ds_bpermute_b32 v248, v244, v23
	s_waitcnt lgkmcnt(0)
	v_cndmask_b32_e64 v181, v247, v248, s[98:99]
	ds_bpermute_b32 v247, v245, v24
	ds_bpermute_b32 v248, v245, v20
	s_waitcnt lgkmcnt(0)
	v_cndmask_b32_e64 v182, v247, v248, s[98:99]
	ds_bpermute_b32 v247, v245, v25
	ds_bpermute_b32 v248, v245, v21
	s_waitcnt lgkmcnt(0)
	v_cndmask_b32_e64 v183, v247, v248, s[98:99]
	ds_bpermute_b32 v247, v245, v26
	ds_bpermute_b32 v248, v245, v22
	s_waitcnt lgkmcnt(0)
	v_cndmask_b32_e64 v184, v247, v248, s[98:99]
	ds_bpermute_b32 v247, v245, v27
	ds_bpermute_b32 v248, v245, v23
	s_waitcnt lgkmcnt(0)
	v_cndmask_b32_e64 v185, v247, v248, s[98:99]
	ds_bpermute_b32 v247, v244, v16
	ds_bpermute_b32 v248, v244, v12
	s_waitcnt lgkmcnt(0)
	v_cndmask_b32_e64 v186, v247, v248, s[98:99]
	ds_bpermute_b32 v247, v244, v17
	ds_bpermute_b32 v248, v244, v13
	s_waitcnt lgkmcnt(0)
; #define LAS __attribute__((address_space(3)))
; #define MFMA16(a, b, c) __builtin_amdgcn_mfma_f32_16x16x32_bf16((a), (b), (c), 0, 0, 0)
; #define S5_CB() asm volatile("" ::: "memory")
; DI void s5_phase(const KArgs& a, int zz, int o, const bf16_t* H, bf16_t* YF, bf16_t* YB, LAS unsigned char* lds, int G, int bid, int wave, int lane) {
;     ...
;         auto loadu = [&](const int ci) __attribute__((always_inline)) -> u32x4 {
;             const int cc = ci < 272 ? ci : 271;
;             u32x4 r = *(const u32x4*)(Hg + (chunk_row(cc) + fr) * D);
;             const bool keep = fq < 2;
;             r.x = keep ? r.x : 0u; r.y = keep ? r.y : 0u; r.z = keep ? r.z : 0u; r.w = keep ? r.w : 0u;
;             return r; };
;         auto stageA = [&](const u32x4 uu) __attribute__((always_inline)) {
;             const bf16x8 Au = __builtin_bit_cast(bf16x8, uu);
; #pragma unroll
;             for (int nt = 0; nt < 8; ++nt) { const f32x4 acc = MFMA16(Bb[nt], Au, ((f32x4){0.f, 0.f, 0.f, 0.f}));
;                 *(LAS f32x4*)(BU + fr * 132 + 16 * nt + fq * 4) = acc; } };
;         u32x4 u1 = loadu(1), u2 = loadu(2);
;         stageA(loadu(0));
;         S5_CB();
	v_cndmask_b32_e64 v187, v247, v248, s[98:99]
	ds_bpermute_b32 v247, v244, v18
	ds_bpermute_b32 v248, v244, v14
	s_waitcnt lgkmcnt(0)
	v_cndmask_b32_e64 v188, v247, v248, s[98:99]
	ds_bpermute_b32 v247, v244, v19
	ds_bpermute_b32 v248, v244, v15
	s_waitcnt lgkmcnt(0)
	v_cndmask_b32_e64 v189, v247, v248, s[98:99]
	ds_bpermute_b32 v247, v245, v16
	ds_bpermute_b32 v248, v245, v12
	s_waitcnt lgkmcnt(0)
	v_cndmask_b32_e64 v190, v247, v248, s[98:99]
	ds_bpermute_b32 v247, v245, v17
	ds_bpermute_b32 v248, v245, v13
	s_waitcnt lgkmcnt(0)
	v_cndmask_b32_e64 v191, v247, v248, s[98:99]
	ds_bpermute_b32 v247, v245, v18
	ds_bpermute_b32 v248, v245, v14
	s_waitcnt lgkmcnt(0)
	v_cndmask_b32_e64 v192, v247, v248, s[98:99]
	ds_bpermute_b32 v247, v245, v19
	ds_bpermute_b32 v248, v245, v15
	s_waitcnt lgkmcnt(0)
	v_cndmask_b32_e64 v193, v247, v248, s[98:99]
	ds_bpermute_b32 v247, v244, v8
	ds_bpermute_b32 v248, v244, v4
	s_waitcnt lgkmcnt(0)
	v_cndmask_b32_e64 v194, v247, v248, s[98:99]
	ds_bpermute_b32 v247, v244, v9
	ds_bpermute_b32 v248, v244, v5
	s_waitcnt lgkmcnt(0)
	v_cndmask_b32_e64 v195, v247, v248, s[98:99]
	ds_bpermute_b32 v247, v244, v10
	ds_bpermute_b32 v248, v244, v6
	s_waitcnt lgkmcnt(0)
	v_cndmask_b32_e64 v196, v247, v248, s[98:99]
	ds_bpermute_b32 v247, v244, v11
	ds_bpermute_b32 v248, v244, v7
	s_waitcnt lgkmcnt(0)
	v_cndmask_b32_e64 v197, v247, v248, s[98:99]
	ds_bpermute_b32 v247, v245, v8
	ds_bpermute_b32 v248, v245, v4
	s_waitcnt lgkmcnt(0)
	v_cndmask_b32_e64 v198, v247, v248, s[98:99]
	ds_bpermute_b32 v247, v245, v9
	ds_bpermute_b32 v248, v245, v5
	s_waitcnt lgkmcnt(0)
	v_cndmask_b32_e64 v199, v247, v248, s[98:99]
	ds_bpermute_b32 v247, v245, v10
	ds_bpermute_b32 v248, v245, v6
	s_waitcnt lgkmcnt(0)
	v_cndmask_b32_e64 v200, v247, v248, s[98:99]
	ds_bpermute_b32 v247, v245, v11
	ds_bpermute_b32 v248, v245, v7
	s_waitcnt lgkmcnt(0)
	v_cndmask_b32_e64 v201, v247, v248, s[98:99]
	ds_bpermute_b32 v247, v244, v0
	ds_bpermute_b32 v248, v244, v28
	s_waitcnt lgkmcnt(0)
	v_cndmask_b32_e64 v202, v247, v248, s[98:99]
	ds_bpermute_b32 v247, v244, v1
	ds_bpermute_b32 v248, v244, v29
	s_waitcnt lgkmcnt(0)
	v_cndmask_b32_e64 v203, v247, v248, s[98:99]
	ds_bpermute_b32 v247, v244, v2
	ds_bpermute_b32 v248, v244, v30
	s_waitcnt lgkmcnt(0)
	v_cndmask_b32_e64 v204, v247, v248, s[98:99]
	ds_bpermute_b32 v247, v244, v3
	ds_bpermute_b32 v248, v244, v31
	s_waitcnt lgkmcnt(0)
	v_cndmask_b32_e64 v205, v247, v248, s[98:99]
	ds_bpermute_b32 v247, v245, v0
	ds_bpermute_b32 v248, v245, v28
	s_waitcnt lgkmcnt(0)
	v_cndmask_b32_e64 v206, v247, v248, s[98:99]
	ds_bpermute_b32 v247, v245, v1
	ds_bpermute_b32 v248, v245, v29
	s_waitcnt lgkmcnt(0)
	v_cndmask_b32_e64 v207, v247, v248, s[98:99]
	ds_bpermute_b32 v247, v245, v2
	ds_bpermute_b32 v248, v245, v30
	s_waitcnt lgkmcnt(0)
	v_cndmask_b32_e64 v208, v247, v248, s[98:99]
	ds_bpermute_b32 v247, v245, v3
	ds_bpermute_b32 v248, v245, v31
	s_waitcnt lgkmcnt(0)
	v_cndmask_b32_e64 v209, v247, v248, s[98:99]
	s_cbranch_vccz .LBB0_413
	s_and_b64 vcc, exec, s[0:1]
	s_cbranch_vccz .LBB0_394
	s_branch .LBB0_416
.LBB0_413:
	v_add_co_u32_e32 v48, vcc, 0x8070000, v130
	v_mov_b32_e32 v123, v122
	s_nop 0
	v_addc_co_u32_e32 v49, vcc, 0, v131, vcc
	global_load_dwordx4 v[48:51], v[48:49], off
	s_add_u32 s0, s54, 0x100f0
	s_addc_u32 s1, s55, 0
	s_ashr_i32 s57, s56, 31
	s_lshl_b64 s[58:59], s[56:57], 12
	s_add_u32 s23, s54, 0x10000
	s_mov_b32 s12, s36
	s_addc_u32 s24, s55, 0
	s_mov_b32 s25, 1
	s_waitcnt vmcnt(0)
	v_cndmask_b32_e64 v72, 0, v48, s[38:39]
	v_add_co_u32_e32 v48, vcc, 0x8068000, v130
	v_cndmask_b32_e64 v73, 0, v49, s[38:39]
	s_nop 0
	v_addc_co_u32_e32 v49, vcc, 0, v131, vcc
	v_add_co_u32_e32 v52, vcc, 0x8078000, v130
	v_cndmask_b32_e64 v74, 0, v50, s[38:39]
	s_nop 0
	v_addc_co_u32_e32 v53, vcc, 0, v131, vcc
	v_cndmask_b32_e64 v75, 0, v51, s[38:39]
	global_load_dwordx4 v[48:51], v[48:49], off
	s_nop 0
	global_load_dwordx4 v[52:55], v[52:53], off
	v_mfma_f32_16x16x32_bf16 v[92:95], v[24:27], v[72:75], 0
	s_waitcnt vmcnt(1)
	v_cndmask_b32_e64 v48, 0, v48, s[38:39]
	v_cndmask_b32_e64 v49, 0, v49, s[38:39]
	s_waitcnt vmcnt(0)
	v_cndmask_b32_e64 v52, 0, v52, s[38:39]
	v_cndmask_b32_e64 v53, 0, v53, s[38:39]
	v_cndmask_b32_e64 v54, 0, v54, s[38:39]
	v_cndmask_b32_e64 v55, 0, v55, s[38:39]
	v_cndmask_b32_e64 v50, 0, v50, s[38:39]
	v_cndmask_b32_e64 v51, 0, v51, s[38:39]
	v_mfma_f32_16x16x32_bf16 v[56:59], v[24:27], v[52:55], 0
	s_nop 7
	ds_write_b128 v157, v[56:59]
	v_mfma_f32_16x16x32_bf16 v[56:59], v[20:23], v[52:55], 0
	s_nop 7
	ds_write_b128 v157, v[56:59] offset:64
	v_mfma_f32_16x16x32_bf16 v[56:59], v[16:19], v[52:55], 0
	s_nop 7
	ds_write_b128 v157, v[56:59] offset:128
	v_mfma_f32_16x16x32_bf16 v[56:59], v[12:15], v[52:55], 0
	s_nop 7
	ds_write_b128 v157, v[56:59] offset:192
	v_mfma_f32_16x16x32_bf16 v[56:59], v[8:11], v[52:55], 0
	s_nop 7
	ds_write_b128 v157, v[56:59] offset:256
	v_mfma_f32_16x16x32_bf16 v[56:59], v[4:7], v[52:55], 0
	s_nop 7
	ds_write_b128 v157, v[56:59] offset:320
	v_mfma_f32_16x16x32_bf16 v[56:59], v[0:3], v[52:55], 0
	v_mfma_f32_16x16x32_bf16 v[52:55], v[28:31], v[52:55], 0
	s_nop 6
	ds_write_b128 v157, v[56:59] offset:384
	ds_write_b128 v157, v[52:55] offset:448
	v_lshl_add_u64 v[52:53], v[110:111], 0, s[54:55]
	v_lshlrev_b64 v[52:53], 11, v[52:53]
	v_lshl_add_u64 v[52:53], v[126:127], 0, v[52:53]
	global_load_dwordx4 v[52:55], v[52:53], off
	ds_read2_b64 v[88:91], v159 offset0:156 offset1:222
	ds_read2_b64 v[84:87], v159 offset0:24 offset1:90
	ds_read2_b64 v[80:83], v160 offset0:148 offset1:214
	ds_read2_b64 v[76:79], v160 offset0:16 offset1:82
	ds_read2_b64 v[68:71], v161 offset0:140 offset1:206
	ds_read2_b64 v[64:67], v161 offset0:8 offset1:74
	ds_read2_b64 v[60:63], v117 offset0:132 offset1:198
	ds_read2_b64 v[56:59], v117 offset1:66
	ds_write_b128 v157, v[92:95]
	v_mfma_f32_16x16x32_bf16 v[92:95], v[20:23], v[72:75], 0
	s_waitcnt vmcnt(0)
; #define LAS __attribute__((address_space(3)))
; DI unsigned pk2(float lo, float hi) { f32x2 v = {lo, hi}; bf16x2_t b = __builtin_convertvector(v, bf16x2_t); return __builtin_bit_cast(unsigned, b); }
; #define MFMA16(a, b, c) __builtin_amdgcn_mfma_f32_16x16x32_bf16((a), (b), (c), 0, 0, 0)
; #define S5_CB() asm volatile("" ::: "memory")
; DI void s5_phase(const KArgs& a, int zz, int o, const bf16_t* H, bf16_t* YF, bf16_t* YB, LAS unsigned char* lds, int G, int bid, int wave, int lane) {
;     ...
;         auto iter = [&](const int ci, const bool do_c) __attribute__((always_inline)) {
;             const size_t row0 = chunk_row(ci);
;             const u32x4 u3 = loadu(ci + 3);
;             f32x2 bu[16];
; #pragma unroll
;             for (int s = 0; s < 16; ++s) { const int tt = DIRC ? 15 - s : s; bu[s] = *(const LAS f32x2*)(BU + tt * 132 + 2 * lane); }
;             bf16x8 Ax[4];
;             if (do_c) {
; #pragma unroll
;                 for (int kb = 0; kb < 4; ++kb) Ax[kb] = *(const LAS bf16x8*)(XS + fr * 68 + kb * 16 + fq * 4); }
;             S5_CB();
;             stageA(u1);
;             S5_CB();
; #pragma unroll
;             for (int s = 0; s < 16; ++s) { const int tt = DIRC ? 15 - s : s;
;                 const float nr = __builtin_fmaf(abr, xr, __builtin_fmaf(nabi, xi, bu[s][0])); const float ni = __builtin_fmaf(abr, xi, __builtin_fmaf(abi, xr, bu[s][1])); xr = nr; xi = ni;
;                 XS[tt * 68 + lane] = pk2(xr, xi); }
;             if (do_c) {
;                 f32x4 ya = (f32x4){0.f, 0.f, 0.f, 0.f};
; #pragma unroll
;                 for (int kb = 0; kb < 4; ++kb) ya = MFMA16(Cb[kb], Ax[kb], ya);
;                 u32x2 w; w.x = pk2(ya[0], ya[1]); w.y = pk2(ya[2], ya[3]); *(u32x2*)(Y + (rowprev + fr) * D + g * 16 + fq * 4) = w; }
;             S5_CB();
;             rowprev = row0; u1 = u2; u2 = u3;
;         };
;         iter(0, false);
	v_cndmask_b32_e64 v52, 0, v52, s[38:39]
	s_nop 5
	ds_write_b128 v157, v[92:95] offset:64
	v_mfma_f32_16x16x32_bf16 v[92:95], v[16:19], v[72:75], 0
	v_cndmask_b32_e64 v53, 0, v53, s[38:39]
	v_cndmask_b32_e64 v54, 0, v54, s[38:39]
	v_cndmask_b32_e64 v55, 0, v55, s[38:39]
	s_nop 4
	ds_write_b128 v157, v[92:95] offset:128
	v_mfma_f32_16x16x32_bf16 v[92:95], v[12:15], v[72:75], 0
	s_nop 7
	ds_write_b128 v157, v[92:95] offset:192
	v_mfma_f32_16x16x32_bf16 v[92:95], v[8:11], v[72:75], 0
	s_nop 7
	ds_write_b128 v157, v[92:95] offset:256
	v_mfma_f32_16x16x32_bf16 v[92:95], v[4:7], v[72:75], 0
	s_nop 7
	ds_write_b128 v157, v[92:95] offset:320
	v_mfma_f32_16x16x32_bf16 v[92:95], v[0:3], v[72:75], 0
	v_mfma_f32_16x16x32_bf16 v[72:75], v[28:31], v[72:75], 0
	s_nop 6
	ds_write_b128 v157, v[92:95] offset:384
	ds_write_b128 v157, v[72:75] offset:448
	s_waitcnt lgkmcnt(14)
	v_fmamk_f32 v72, v125, 0x80000000, v90
	v_fma_f32 v73, 0, v125, v91
	v_fmac_f32_e32 v72, 0, v122
	v_fmac_f32_e32 v73, 0, v122
	v_fma_f32 v75, -v125, v73, v88
	v_fmac_f32_e32 v89, v125, v72
	v_fmac_f32_e32 v75, v122, v72
	v_fmac_f32_e32 v89, v122, v73
	v_cvt_pk_bf16_f32 v74, v72, v73
	v_cvt_pk_bf16_f32 v72, v75, v89
	ds_write2_b32 v162, v72, v74 offset0:120 offset1:188
	v_fma_f32 v72, -v125, v89, v86
	v_fma_f32 v73, v125, v75, v87
	v_fmac_f32_e32 v72, v122, v75
	v_fmac_f32_e32 v73, v122, v89
	v_fma_f32 v75, -v125, v73, v84
	v_fmac_f32_e32 v85, v125, v72
	v_fmac_f32_e32 v75, v122, v72
	v_fmac_f32_e32 v85, v122, v73
	v_cvt_pk_bf16_f32 v74, v72, v73
	v_cvt_pk_bf16_f32 v72, v75, v85
	ds_write2_b32 v163, v72, v74 offset0:112 offset1:180
	s_waitcnt lgkmcnt(14)
	v_fma_f32 v72, -v125, v85, v82
	v_fma_f32 v73, v125, v75, v83
	v_fmac_f32_e32 v72, v122, v75
	v_fmac_f32_e32 v73, v122, v85
	v_fma_f32 v75, -v125, v73, v80
	v_fmac_f32_e32 v81, v125, v72
	v_fmac_f32_e32 v75, v122, v72
	v_fmac_f32_e32 v81, v122, v73
	v_cvt_pk_bf16_f32 v74, v72, v73
	v_cvt_pk_bf16_f32 v72, v75, v81
	ds_write2_b32 v164, v72, v74 offset0:104 offset1:172
	v_fma_f32 v72, -v125, v81, v78
	v_fma_f32 v73, v125, v75, v79
	v_fmac_f32_e32 v72, v122, v75
	v_fmac_f32_e32 v73, v122, v81
	v_fma_f32 v75, -v125, v73, v76
	v_fmac_f32_e32 v77, v125, v72
	v_fmac_f32_e32 v75, v122, v72
	v_fmac_f32_e32 v77, v122, v73
	s_waitcnt lgkmcnt(14)
	v_fma_f32 v70, -v125, v77, v70
	v_fma_f32 v71, v125, v75, v71
	v_fmac_f32_e32 v70, v122, v75
	v_fmac_f32_e32 v71, v122, v77
	v_fma_f32 v68, -v125, v71, v68
	v_fmac_f32_e32 v69, v125, v70
	v_fmac_f32_e32 v68, v122, v70
	v_fmac_f32_e32 v69, v122, v71
	s_waitcnt lgkmcnt(13)
	v_fma_f32 v66, -v125, v69, v66
	v_fma_f32 v67, v125, v68, v67
	v_fmac_f32_e32 v66, v122, v68
	v_fmac_f32_e32 v67, v122, v69
	v_fma_f32 v64, -v125, v67, v64
	v_fmac_f32_e32 v65, v125, v66
	v_fmac_f32_e32 v64, v122, v66
	v_fmac_f32_e32 v65, v122, v67
	s_waitcnt lgkmcnt(12)
	v_fma_f32 v62, -v125, v65, v62
	v_fma_f32 v63, v125, v64, v63
	v_fmac_f32_e32 v62, v122, v64
	v_fmac_f32_e32 v63, v122, v65
	v_fma_f32 v60, -v125, v63, v60
	v_fmac_f32_e32 v61, v125, v62
	v_cvt_pk_bf16_f32 v74, v72, v73
	v_cvt_pk_bf16_f32 v72, v75, v77
	v_fmac_f32_e32 v60, v122, v62
	v_fmac_f32_e32 v61, v122, v63
	ds_write2_b32 v165, v72, v74 offset0:96 offset1:164
	v_cvt_pk_bf16_f32 v72, v70, v71
	v_cvt_pk_bf16_f32 v70, v68, v69
	v_cvt_pk_bf16_f32 v68, v66, v67
	v_cvt_pk_bf16_f32 v66, v64, v65
	v_cvt_pk_bf16_f32 v64, v62, v63
	v_cvt_pk_bf16_f32 v62, v60, v61
	ds_write2_b32 v168, v62, v64 offset0:72 offset1:140
	s_waitcnt lgkmcnt(13)
	v_fma_f32 v63, -v125, v61, v58
	v_fma_f32 v62, v125, v60, v59
	v_fmac_f32_e32 v63, v122, v60
	v_fmac_f32_e32 v62, v122, v61
	v_mov_b32_e32 v60, v125
	v_pk_fma_f32 v[56:57], v[60:61], v[62:63], v[56:57] op_sel_hi:[0,1,1] neg_lo:[1,0,0]
	v_mov_b32_e32 v60, v63
	v_mov_b32_e32 v61, v62
	v_pk_fma_f32 v[132:133], v[122:123], v[60:61], v[56:57] op_sel_hi:[0,1,1]
	v_cvt_pk_bf16_f32 v58, v63, v62
	v_cvt_pk_bf16_f32 v56, v132, v133
	ds_write2_b32 v166, v70, v72 offset0:88 offset1:156
	ds_write2_b32 v167, v66, v68 offset0:80 offset1:148
	ds_write2_b32 v169, v56, v58 offset0:64 offset1:132
	ds_read_b64 v[100:101], v159 offset:1248
	ds_read_b64 v[102:103], v159 offset:1776
	ds_read_b64 v[96:97], v159 offset:192
	ds_read_b64 v[98:99], v159 offset:720
	ds_read_b64 v[92:93], v160 offset:1184
	ds_read_b64 v[94:95], v160 offset:1712
	ds_read_b64 v[88:89], v160 offset:128
	ds_read_b64 v[90:91], v160 offset:656
	ds_read_b64 v[84:85], v161 offset:1120
	ds_read_b64 v[86:87], v161 offset:1648
	ds_read_b64 v[80:81], v161 offset:64
	ds_read_b64 v[82:83], v161 offset:592
	ds_read_b64 v[76:77], v117 offset:1056
	ds_read_b64 v[78:79], v117 offset:1584
	ds_read_b64 v[72:73], v117
	ds_read_b64 v[74:75], v117 offset:528
	s_waitcnt lgkmcnt(0)
	v_mov_b32_e32 v214, v72
	v_mov_b32_e32 v218, v73
	v_mov_b32_e32 v215, v74
	v_mov_b32_e32 v219, v75
	v_mov_b32_e32 v216, v76
	v_mov_b32_e32 v220, v77
	v_mov_b32_e32 v217, v78
	v_mov_b32_e32 v221, v79
	v_mov_b32_e32 v222, v80
	v_mov_b32_e32 v226, v81
	v_mov_b32_e32 v223, v82
	v_mov_b32_e32 v227, v83
	v_mov_b32_e32 v224, v84
	v_mov_b32_e32 v228, v85
	v_mov_b32_e32 v225, v86
	v_mov_b32_e32 v229, v87
	v_mov_b32_e32 v230, v88
	v_mov_b32_e32 v234, v89
	v_mov_b32_e32 v231, v90
	v_mov_b32_e32 v235, v91
	v_mov_b32_e32 v232, v92
	v_mov_b32_e32 v236, v93
	v_mov_b32_e32 v233, v94
	v_mov_b32_e32 v237, v95
	v_mov_b32_e32 v238, v96
	v_mov_b32_e32 v242, v97
	v_mov_b32_e32 v239, v98
	v_mov_b32_e32 v243, v99
	v_mov_b32_e32 v240, v100
	v_mov_b32_e32 v244, v101
	v_mov_b32_e32 v241, v102
	v_mov_b32_e32 v245, v103
; #define LAS __attribute__((address_space(3)))
; DI unsigned pk2(float lo, float hi) { f32x2 v = {lo, hi}; bf16x2_t b = __builtin_convertvector(v, bf16x2_t); return __builtin_bit_cast(unsigned, b); }
; #define MFMA16(a, b, c) __builtin_amdgcn_mfma_f32_16x16x32_bf16((a), (b), (c), 0, 0, 0)
; #define S5_CB() asm volatile("" ::: "memory")
; DI void s5_phase(const KArgs& a, int zz, int o, const bf16_t* H, bf16_t* YF, bf16_t* YB, LAS unsigned char* lds, int G, int bid, int wave, int lane) {
;     ...
;         auto iter = [&](const int ci, const bool do_c) __attribute__((always_inline)) {
;             const size_t row0 = chunk_row(ci);
;             const u32x4 u3 = loadu(ci + 3);
;             f32x2 bu[16];
; #pragma unroll
;             for (int s = 0; s < 16; ++s) { const int tt = DIRC ? 15 - s : s; bu[s] = *(const LAS f32x2*)(BU + tt * 132 + 2 * lane); }
;             bf16x8 Ax[4];
;             if (do_c) {
; #pragma unroll
;                 for (int kb = 0; kb < 4; ++kb) Ax[kb] = *(const LAS bf16x8*)(XS + fr * 68 + kb * 16 + fq * 4); }
;             S5_CB();
;             stageA(u1);
;             S5_CB();
; #pragma unroll
;             for (int s = 0; s < 16; ++s) { const int tt = DIRC ? 15 - s : s;
;                 const float nr = __builtin_fmaf(abr, xr, __builtin_fmaf(nabi, xi, bu[s][0])); const float ni = __builtin_fmaf(abr, xi, __builtin_fmaf(abi, xr, bu[s][1])); xr = nr; xi = ni;
;                 XS[tt * 68 + lane] = pk2(xr, xi); }
;             if (do_c) {
;                 f32x4 ya = (f32x4){0.f, 0.f, 0.f, 0.f};
; #pragma unroll
;                 for (int kb = 0; kb < 4; ++kb) ya = MFMA16(Cb[kb], Ax[kb], ya);
;                 u32x2 w; w.x = pk2(ya[0], ya[1]); w.y = pk2(ya[2], ya[3]); *(u32x2*)(Y + (rowprev + fr) * D + g * 16 + fq * 4) = w; }
;             S5_CB();
;             rowprev = row0; u1 = u2; u2 = u3;
;         };
;         iter(0, false);
;         for (int ci = 1; ci < 272; ++ci) iter(ci, true);
.LBB0_414:
	s_waitcnt vmcnt(1)
	v_cndmask_b32_e64 v173, 0, v52, s[38:39]
	v_sub_co_u32_e64 v52, s[26:27], s25, 16
	s_and_b64 s[30:31], s[26:27], exec
	v_readfirstlane_b32 s30, v52
	s_cselect_b32 s30, s25, s30
	s_cselect_b32 s31, 15, 0xff
	s_sub_i32 s30, s31, s30
	s_lshl_b32 s30, s30, 4
	s_ashr_i32 s31, s30, 31
	s_and_b64 s[26:27], s[26:27], exec
	s_cselect_b32 s26, s23, s58
	s_cselect_b32 s27, s24, s59
	s_add_u32 s26, s26, s30
	s_addc_u32 s27, s27, s31
	s_min_i32 s36, s25, 0x10c
	s_cmp_lt_u32 s25, 13
	s_cselect_b64 s[30:31], -1, 0
	s_and_b64 s[34:35], s[30:31], exec
	s_cselect_b32 s34, -3, 13
	s_cselect_b32 s35, 15, 0xff
	s_sub_i32 s34, s34, s36
	s_add_i32 s34, s34, s35
	s_lshl_b32 s34, s34, 4
	s_ashr_i32 s35, s34, 31
	s_and_b64 s[30:31], s[30:31], exec
	s_cselect_b32 s31, s23, s58
	s_cselect_b32 s30, s24, s59
	s_add_u32 s31, s31, s34
	s_addc_u32 s30, s30, s35
	v_cndmask_b32_e64 v172, 0, v53, s[38:39]
	v_mov_b32_e32 v53, s30
	v_or_b32_e32 v52, s31, v104
	v_lshlrev_b64 v[52:53], 11, v[52:53]
	v_lshl_add_u64 v[52:53], v[126:127], 0, v[52:53]
	v_add_u32_e32 v148, v134, v107
	v_cndmask_b32_e64 v170, 0, v55, s[38:39]
	v_cndmask_b32_e64 v171, 0, v54, s[38:39]
	global_load_dwordx4 v[52:55], v[52:53], off
	ds_read_b128 v[56:59], v148 offset:8448
	ds_read_b128 v[60:63], v148 offset:8512
	ds_read_b128 v[64:67], v148 offset:8576
	ds_read_b128 v[68:71], v148 offset:8640
	s_waitcnt lgkmcnt(0)
	v_mfma_f32_16x16x32_bf16 v[56:59], v[32:35], v[56:59], 0
	v_mfma_f32_16x16x32_bf16 v[56:59], v[36:39], v[60:63], v[56:59]
	v_mfma_f32_16x16x32_bf16 v[56:59], v[40:43], v[64:67], v[56:59]
	v_mfma_f32_16x16x32_bf16 v[56:59], v[44:47], v[68:71], v[56:59]
	v_fma_f32 v60, -v125, v133, v241
	v_fma_f32 v61, v125, v132, v245
	v_fmac_f32_e32 v60, v122, v132
	v_fmac_f32_e32 v61, v122, v133
	v_fma_f32 v63, -v125, v61, v240
	v_fmac_f32_e32 v244, v125, v60
	v_fmac_f32_e32 v63, v122, v60
	v_fmac_f32_e32 v244, v122, v61
	v_cvt_pk_bf16_f32 v62, v60, v61
	v_cvt_pk_bf16_f32 v60, v63, v244
	ds_write2_b32 v162, v60, v62 offset0:120 offset1:188
	v_fma_f32 v60, -v125, v244, v239
	v_fma_f32 v61, v125, v63, v243
	v_fmac_f32_e32 v60, v122, v63
	v_fmac_f32_e32 v61, v122, v244
	v_fma_f32 v63, -v125, v61, v238
	v_fmac_f32_e32 v242, v125, v60
	v_fmac_f32_e32 v63, v122, v60
	v_fmac_f32_e32 v242, v122, v61
	v_cvt_pk_bf16_f32 v62, v60, v61
	v_cvt_pk_bf16_f32 v60, v63, v242
	ds_write2_b32 v163, v60, v62 offset0:112 offset1:180
	v_fma_f32 v60, -v125, v242, v233
	v_fma_f32 v61, v125, v63, v237
	v_fmac_f32_e32 v60, v122, v63
	v_fmac_f32_e32 v61, v122, v242
	v_fma_f32 v63, -v125, v61, v232
	v_fmac_f32_e32 v236, v125, v60
	v_fmac_f32_e32 v63, v122, v60
	v_fmac_f32_e32 v236, v122, v61
	v_cvt_pk_bf16_f32 v62, v60, v61
	v_cvt_pk_bf16_f32 v60, v63, v236
	ds_write2_b32 v164, v60, v62 offset0:104 offset1:172
	v_fma_f32 v60, -v125, v236, v231
	v_fma_f32 v61, v125, v63, v235
	v_fmac_f32_e32 v60, v122, v63
	v_fmac_f32_e32 v61, v122, v236
	v_fma_f32 v63, -v125, v61, v230
	v_fmac_f32_e32 v234, v125, v60
	v_fmac_f32_e32 v63, v122, v60
	v_fmac_f32_e32 v234, v122, v61
	v_cvt_pk_bf16_f32 v62, v60, v61
	v_cvt_pk_bf16_f32 v60, v63, v234
	ds_write2_b32 v165, v60, v62 offset0:96 offset1:164
	v_fma_f32 v60, -v125, v234, v225
	v_fma_f32 v61, v125, v63, v229
	v_fmac_f32_e32 v60, v122, v63
	v_fmac_f32_e32 v61, v122, v234
	v_fma_f32 v63, -v125, v61, v224
	v_fmac_f32_e32 v228, v125, v60
	v_fmac_f32_e32 v63, v122, v60
	v_fmac_f32_e32 v228, v122, v61
	v_cvt_pk_bf16_f32 v62, v60, v61
	v_cvt_pk_bf16_f32 v60, v63, v228
	ds_write2_b32 v166, v60, v62 offset0:88 offset1:156
	v_fma_f32 v60, -v125, v228, v223
	v_fma_f32 v61, v125, v63, v227
	v_fmac_f32_e32 v60, v122, v63
	v_fmac_f32_e32 v61, v122, v228
	v_fma_f32 v63, -v125, v61, v222
	v_fmac_f32_e32 v226, v125, v60
	v_fmac_f32_e32 v63, v122, v60
	v_fmac_f32_e32 v226, v122, v61
	v_cvt_pk_bf16_f32 v62, v60, v61
	v_cvt_pk_bf16_f32 v60, v63, v226
	ds_write2_b32 v167, v60, v62 offset0:80 offset1:148
	v_fma_f32 v60, -v125, v226, v217
	v_fma_f32 v61, v125, v63, v221
	v_fmac_f32_e32 v60, v122, v63
	v_fmac_f32_e32 v61, v122, v226
	v_fma_f32 v63, -v125, v61, v216
	v_fmac_f32_e32 v220, v125, v60
	v_fmac_f32_e32 v63, v122, v60
	v_fmac_f32_e32 v220, v122, v61
	v_cvt_pk_bf16_f32 v62, v60, v61
	v_cvt_pk_bf16_f32 v60, v63, v220
	ds_write2_b32 v168, v60, v62 offset0:72 offset1:140
	v_fma_f32 v60, -v125, v220, v215
	v_fma_f32 v61, v125, v63, v219
	v_fmac_f32_e32 v60, v122, v63
	v_fmac_f32_e32 v61, v122, v220
	v_fma_f32 v63, -v125, v61, v214
	v_fmac_f32_e32 v218, v125, v60
	v_fmac_f32_e32 v63, v122, v60
	v_fmac_f32_e32 v218, v122, v61
	v_cvt_pk_bf16_f32 v62, v60, v61
	v_cvt_pk_bf16_f32 v60, v63, v218
	ds_write2_b32 v169, v60, v62 offset0:64 offset1:132
	v_mov_b32_e32 v132, v63
	v_mov_b32_e32 v133, v218
	v_mfma_f32_16x16x32_bf16 v[214:217], v[48:51], v[178:181], 0
	v_mfma_f32_16x16x32_bf16 v[222:225], v[48:51], v[186:189], 0
	v_mfma_f32_16x16x32_bf16 v[230:233], v[48:51], v[194:197], 0
	v_mfma_f32_16x16x32_bf16 v[238:241], v[48:51], v[202:205], 0
	v_mfma_f32_16x16x32_bf16 v[218:221], v[48:51], v[182:185], 0
	v_mfma_f32_16x16x32_bf16 v[226:229], v[48:51], v[190:193], 0
	v_mfma_f32_16x16x32_bf16 v[234:237], v[48:51], v[198:201], 0
	v_mfma_f32_16x16x32_bf16 v[242:245], v[48:51], v[206:209], 0
	v_cvt_pk_bf16_f32 v56, v56, v57
	v_cvt_pk_bf16_f32 v57, v58, v59
	v_lshl_add_u64 v[62:63], s[0:1], 0, v[104:105]
	v_lshlrev_b64 v[62:63], 11, v[62:63]
	v_lshl_add_u64 v[62:63], v[128:129], 0, v[62:63]
	global_store_dwordx2 v[62:63], v[56:57], off
	v_permlane32_swap_b32_e32 v214, v230
	v_permlane32_swap_b32_e32 v222, v238
	v_permlane32_swap_b32_e32 v215, v231
	v_permlane32_swap_b32_e32 v223, v239
	v_permlane32_swap_b32_e32 v216, v232
	v_permlane32_swap_b32_e32 v224, v240
	v_permlane32_swap_b32_e32 v217, v233
	v_permlane32_swap_b32_e32 v225, v241
	v_permlane16_swap_b32_e32 v214, v222
	v_permlane16_swap_b32_e32 v230, v238
	v_permlane16_swap_b32_e32 v215, v223
	v_permlane16_swap_b32_e32 v231, v239
	v_permlane16_swap_b32_e32 v216, v224
	v_permlane16_swap_b32_e32 v232, v240
	v_permlane16_swap_b32_e32 v217, v225
	v_permlane16_swap_b32_e32 v233, v241
	v_permlane32_swap_b32_e32 v218, v234
	v_permlane32_swap_b32_e32 v226, v242
	v_permlane32_swap_b32_e32 v219, v235
	v_permlane32_swap_b32_e32 v227, v243
	v_permlane32_swap_b32_e32 v220, v236
	v_permlane32_swap_b32_e32 v228, v244
	v_permlane32_swap_b32_e32 v221, v237
	v_permlane32_swap_b32_e32 v229, v245
	v_permlane16_swap_b32_e32 v218, v226
	v_permlane16_swap_b32_e32 v234, v242
	v_permlane16_swap_b32_e32 v219, v227
	v_permlane16_swap_b32_e32 v235, v243
	v_permlane16_swap_b32_e32 v220, v228
	v_permlane16_swap_b32_e32 v236, v244
	v_permlane16_swap_b32_e32 v221, v229
	v_permlane16_swap_b32_e32 v237, v245
	s_mov_b64 s[0:1], s[26:27]
	v_mov_b32_e32 v48, v173
	v_mov_b32_e32 v49, v172
	v_mov_b32_e32 v50, v171
	v_mov_b32_e32 v51, v170
	s_add_i32 s25, s25, 1
	s_cmpk_lg_i32 s25, 0x110
	s_cbranch_scc1 .LBB0_414
; DI void s5_phase(const KArgs& a, int zz, int o, const bf16_t* H, bf16_t* YF, bf16_t* YB, LAS unsigned char* lds, int G, int bid, int wave, int lane) {
;     ...
;         auto loadu = [&](const int ci) __attribute__((always_inline)) -> u32x4 {
;             const int cc = ci < 272 ? ci : 271;
;             u32x4 r = *(const u32x4*)(Hg + (chunk_row(cc) + fr) * D);
;             const bool keep = fq < 2;
;             r.x = keep ? r.x : 0u; r.y = keep ? r.y : 0u; r.z = keep ? r.z : 0u; r.w = keep ? r.w : 0u;
;             return r; };
;         auto stageA = [&](const u32x4 uu) __attribute__((always_inline)) {
;             const bf16x8 Au = __builtin_bit_cast(bf16x8, uu);
; #pragma unroll
;             for (int nt = 0; nt < 8; ++nt) { const f32x4 acc = MFMA16(Bb[nt], Au, ((f32x4){0.f, 0.f, 0.f, 0.f}));
;                 *(LAS f32x4*)(BU + fr * 132 + 16 * nt + fq * 4) = acc; } };
;         u32x4 u1 = loadu(1), u2 = loadu(2);
;         stageA(loadu(0));
;         S5_CB();
;         size_t rowprev = 0;
;         auto iter = [&](const int ci, const bool do_c) __attribute__((always_inline)) {
;             const size_t row0 = chunk_row(ci);
;             const u32x4 u3 = loadu(ci + 3);
;             f32x2 bu[16];
; #pragma unroll
;             for (int s = 0; s < 16; ++s) { const int tt = DIRC ? 15 - s : s; bu[s] = *(const LAS f32x2*)(BU + tt * 132 + 2 * lane); }
;             bf16x8 Ax[4];
;             if (do_c) {
; #pragma unroll
;                 for (int kb = 0; kb < 4; ++kb) Ax[kb] = *(const LAS bf16x8*)(XS + fr * 68 + kb * 16 + fq * 4); }
;             S5_CB();
;             stageA(u1);
;             S5_CB();
; #pragma unroll
;             for (int s = 0; s < 16; ++s) { const int tt = DIRC ? 15 - s : s;
;                 const float nr = __builtin_fmaf(abr, xr, __builtin_fmaf(nabi, xi, bu[s][0])); const float ni = __builtin_fmaf(abr, xi, __builtin_fmaf(abi, xr, bu[s][1])); xr = nr; xi = ni;
;                 XS[tt * 68 + lane] = pk2(xr, xi); }
;             if (do_c) {
;                 f32x4 ya = (f32x4){0.f, 0.f, 0.f, 0.f};
; #pragma unroll
;                 for (int kb = 0; kb < 4; ++kb) ya = MFMA16(Cb[kb], Ax[kb], ya);
;                 u32x2 w; w.x = pk2(ya[0], ya[1]); w.y = pk2(ya[2], ya[3]); *(u32x2*)(Y + (rowprev + fr) * D + g * 16 + fq * 4) = w; }
;             S5_CB();
;             rowprev = row0; u1 = u2; u2 = u3;
;         };
;         iter(0, false);
	s_waitcnt vmcnt(0)
	ds_read_b128 v[48:51], v148 offset:8448
	ds_read_b128 v[52:55], v148 offset:8512
	s_mov_b32 s36, s12
	s_waitcnt lgkmcnt(1)
	v_mfma_f32_16x16x32_bf16 v[48:51], v[32:35], v[48:51], 0
	s_waitcnt lgkmcnt(0)
	v_mfma_f32_16x16x32_bf16 v[48:51], v[36:39], v[52:55], v[48:51]
	ds_read_b128 v[52:55], v148 offset:8576
	s_waitcnt lgkmcnt(0)
	v_mfma_f32_16x16x32_bf16 v[48:51], v[40:43], v[52:55], v[48:51]
	ds_read_b128 v[52:55], v148 offset:8640
	v_lshlrev_b32_e32 v148, 1, v106
	s_waitcnt lgkmcnt(0)
	v_mfma_f32_16x16x32_bf16 v[48:51], v[44:47], v[52:55], v[48:51]
	s_nop 7
	v_cvt_pk_bf16_f32 v48, v48, v49
	v_cvt_pk_bf16_f32 v49, v50, v51
	v_mov_b32_e32 v51, s27
	v_or_b32_e32 v50, s26, v104
	v_lshlrev_b64 v[50:51], 11, v[50:51]
	v_lshl_add_u64 v[50:51], s[6:7], 0, v[50:51]
	v_lshl_add_u64 v[50:51], s[52:53], 1, v[50:51]
	v_lshl_add_u64 v[50:51], v[50:51], 0, v[148:149]
	global_store_dwordx2 v[50:51], v[48:49], off
	s_waitcnt lgkmcnt(0)
	s_branch .LBB0_394
.LBB0_416:
	v_add_co_u32_e32 v48, vcc, 0x8008000, v130
	v_mov_b32_e32 v123, v122
	s_nop 0
	v_addc_co_u32_e32 v49, vcc, 0, v131, vcc
	global_load_dwordx4 v[48:51], v[48:49], off
	s_add_u32 s0, s54, 0x10000
	s_addc_u32 s1, s55, 0
	s_ashr_i32 s57, s56, 31
	s_lshl_b64 s[56:57], s[56:57], 12
	s_mov_b32 s23, 1
	s_mov_b32 s24, 0x10010
	s_waitcnt vmcnt(0)
	v_cndmask_b32_e64 v72, 0, v48, s[38:39]
	v_add_co_u32_e32 v48, vcc, 0x8010000, v130
	v_cndmask_b32_e64 v73, 0, v49, s[38:39]
	s_nop 0
	v_addc_co_u32_e32 v49, vcc, 0, v131, vcc
	v_add_co_u32_e32 v52, vcc, 0x8000000, v130
	v_cndmask_b32_e64 v74, 0, v50, s[38:39]
	s_nop 0
	v_addc_co_u32_e32 v53, vcc, 0, v131, vcc
	v_cndmask_b32_e64 v75, 0, v51, s[38:39]
	global_load_dwordx4 v[48:51], v[48:49], off
	s_nop 0
	global_load_dwordx4 v[52:55], v[52:53], off
	v_mfma_f32_16x16x32_bf16 v[92:95], v[24:27], v[72:75], 0
	s_waitcnt vmcnt(1)
	v_cndmask_b32_e64 v48, 0, v48, s[38:39]
	v_cndmask_b32_e64 v49, 0, v49, s[38:39]
	s_waitcnt vmcnt(0)
	v_cndmask_b32_e64 v52, 0, v52, s[38:39]
	v_cndmask_b32_e64 v53, 0, v53, s[38:39]
	v_cndmask_b32_e64 v54, 0, v54, s[38:39]
	v_cndmask_b32_e64 v55, 0, v55, s[38:39]
	v_cndmask_b32_e64 v50, 0, v50, s[38:39]
	v_cndmask_b32_e64 v51, 0, v51, s[38:39]
	v_mfma_f32_16x16x32_bf16 v[56:59], v[24:27], v[52:55], 0
	s_nop 7
	ds_write_b128 v157, v[56:59]
	v_mfma_f32_16x16x32_bf16 v[56:59], v[20:23], v[52:55], 0
	s_nop 7
	ds_write_b128 v157, v[56:59] offset:64
	v_mfma_f32_16x16x32_bf16 v[56:59], v[16:19], v[52:55], 0
	s_nop 7
	ds_write_b128 v157, v[56:59] offset:128
	v_mfma_f32_16x16x32_bf16 v[56:59], v[12:15], v[52:55], 0
	s_nop 7
	ds_write_b128 v157, v[56:59] offset:192
	v_mfma_f32_16x16x32_bf16 v[56:59], v[8:11], v[52:55], 0
	s_nop 7
	ds_write_b128 v157, v[56:59] offset:256
	v_mfma_f32_16x16x32_bf16 v[56:59], v[4:7], v[52:55], 0
	s_nop 7
	ds_write_b128 v157, v[56:59] offset:320
	v_mfma_f32_16x16x32_bf16 v[56:59], v[0:3], v[52:55], 0
	v_mfma_f32_16x16x32_bf16 v[52:55], v[28:31], v[52:55], 0
	s_nop 6
	ds_write_b128 v157, v[56:59] offset:384
	ds_write_b128 v157, v[52:55] offset:448
	v_lshl_add_u64 v[52:53], v[114:115], 0, s[54:55]
	v_lshlrev_b64 v[52:53], 11, v[52:53]
	v_lshl_add_u64 v[52:53], v[126:127], 0, v[52:53]
	global_load_dwordx4 v[52:55], v[52:53], off
	ds_read2_b64 v[88:91], v117 offset1:66
	ds_read2_b64 v[84:87], v117 offset0:132 offset1:198
	ds_read2_b64 v[80:83], v161 offset0:8 offset1:74
	ds_read2_b64 v[76:79], v161 offset0:140 offset1:206
	ds_read2_b64 v[68:71], v160 offset0:16 offset1:82
	ds_read2_b64 v[64:67], v160 offset0:148 offset1:214
	ds_read2_b64 v[60:63], v159 offset0:24 offset1:90
	ds_read2_b64 v[56:59], v159 offset0:156 offset1:222
	ds_write_b128 v157, v[92:95]
	v_mfma_f32_16x16x32_bf16 v[92:95], v[20:23], v[72:75], 0
	s_waitcnt vmcnt(0)
	v_cndmask_b32_e64 v52, 0, v52, s[38:39]
	s_nop 5
	ds_write_b128 v157, v[92:95] offset:64
	v_mfma_f32_16x16x32_bf16 v[92:95], v[16:19], v[72:75], 0
	v_cndmask_b32_e64 v53, 0, v53, s[38:39]
	v_cndmask_b32_e64 v54, 0, v54, s[38:39]
	v_cndmask_b32_e64 v55, 0, v55, s[38:39]
	s_nop 4
	ds_write_b128 v157, v[92:95] offset:128
	v_mfma_f32_16x16x32_bf16 v[92:95], v[12:15], v[72:75], 0
	s_nop 7
	ds_write_b128 v157, v[92:95] offset:192
	v_mfma_f32_16x16x32_bf16 v[92:95], v[8:11], v[72:75], 0
	s_nop 7
	ds_write_b128 v157, v[92:95] offset:256
	v_mfma_f32_16x16x32_bf16 v[92:95], v[4:7], v[72:75], 0
	s_nop 7
	ds_write_b128 v157, v[92:95] offset:320
	v_mfma_f32_16x16x32_bf16 v[92:95], v[0:3], v[72:75], 0
	v_mfma_f32_16x16x32_bf16 v[72:75], v[28:31], v[72:75], 0
	s_nop 6
	ds_write_b128 v157, v[92:95] offset:384
	ds_write_b128 v157, v[72:75] offset:448
	s_waitcnt lgkmcnt(14)
	v_fmamk_f32 v72, v125, 0x80000000, v88
	v_fma_f32 v73, 0, v125, v89
	v_fmac_f32_e32 v72, 0, v122
	v_fmac_f32_e32 v73, 0, v122
	v_fma_f32 v75, -v125, v73, v90
	v_fmac_f32_e32 v91, v125, v72
	v_fmac_f32_e32 v75, v122, v72
	v_fmac_f32_e32 v91, v122, v73
	v_cvt_pk_bf16_f32 v74, v72, v73
	v_cvt_pk_bf16_f32 v72, v75, v91
	ds_write2_b32 v169, v74, v72 offset0:64 offset1:132
	v_fma_f32 v72, -v125, v91, v84
	v_fma_f32 v73, v125, v75, v85
	v_fmac_f32_e32 v72, v122, v75
	v_fmac_f32_e32 v73, v122, v91
	v_fma_f32 v75, -v125, v73, v86
	v_fmac_f32_e32 v87, v125, v72
	v_fmac_f32_e32 v75, v122, v72
	v_fmac_f32_e32 v87, v122, v73
	v_cvt_pk_bf16_f32 v74, v72, v73
	v_cvt_pk_bf16_f32 v72, v75, v87
	ds_write2_b32 v168, v74, v72 offset0:72 offset1:140
	s_waitcnt lgkmcnt(14)
; #define LAS __attribute__((address_space(3)))
; DI unsigned pk2(float lo, float hi) { f32x2 v = {lo, hi}; bf16x2_t b = __builtin_convertvector(v, bf16x2_t); return __builtin_bit_cast(unsigned, b); }
; #define MFMA16(a, b, c) __builtin_amdgcn_mfma_f32_16x16x32_bf16((a), (b), (c), 0, 0, 0)
; #define S5_CB() asm volatile("" ::: "memory")
; DI void s5_phase(const KArgs& a, int zz, int o, const bf16_t* H, bf16_t* YF, bf16_t* YB, LAS unsigned char* lds, int G, int bid, int wave, int lane) {
;     ...
;         auto iter = [&](const int ci, const bool do_c) __attribute__((always_inline)) {
;             const size_t row0 = chunk_row(ci);
;             const u32x4 u3 = loadu(ci + 3);
;             f32x2 bu[16];
; #pragma unroll
;             for (int s = 0; s < 16; ++s) { const int tt = DIRC ? 15 - s : s; bu[s] = *(const LAS f32x2*)(BU + tt * 132 + 2 * lane); }
;             bf16x8 Ax[4];
;             if (do_c) {
; #pragma unroll
;                 for (int kb = 0; kb < 4; ++kb) Ax[kb] = *(const LAS bf16x8*)(XS + fr * 68 + kb * 16 + fq * 4); }
;             S5_CB();
;             stageA(u1);
;             S5_CB();
; #pragma unroll
;             for (int s = 0; s < 16; ++s) { const int tt = DIRC ? 15 - s : s;
;                 const float nr = __builtin_fmaf(abr, xr, __builtin_fmaf(nabi, xi, bu[s][0])); const float ni = __builtin_fmaf(abr, xi, __builtin_fmaf(abi, xr, bu[s][1])); xr = nr; xi = ni;
;                 XS[tt * 68 + lane] = pk2(xr, xi); }
;             if (do_c) {
;                 f32x4 ya = (f32x4){0.f, 0.f, 0.f, 0.f};
; #pragma unroll
;                 for (int kb = 0; kb < 4; ++kb) ya = MFMA16(Cb[kb], Ax[kb], ya);
;                 u32x2 w; w.x = pk2(ya[0], ya[1]); w.y = pk2(ya[2], ya[3]); *(u32x2*)(Y + (rowprev + fr) * D + g * 16 + fq * 4) = w; }
	v_fma_f32 v72, -v125, v87, v80
	v_fma_f32 v73, v125, v75, v81
	v_fmac_f32_e32 v72, v122, v75
	v_fmac_f32_e32 v73, v122, v87
	v_fma_f32 v75, -v125, v73, v82
	v_fmac_f32_e32 v83, v125, v72
	v_fmac_f32_e32 v75, v122, v72
	v_fmac_f32_e32 v83, v122, v73
	v_cvt_pk_bf16_f32 v74, v72, v73
	v_cvt_pk_bf16_f32 v72, v75, v83
	ds_write2_b32 v167, v74, v72 offset0:80 offset1:148
	v_fma_f32 v72, -v125, v83, v76
	v_fma_f32 v73, v125, v75, v77
	v_fmac_f32_e32 v72, v122, v75
	v_fmac_f32_e32 v73, v122, v83
	v_fma_f32 v75, -v125, v73, v78
	v_fmac_f32_e32 v79, v125, v72
	v_fmac_f32_e32 v75, v122, v72
	v_fmac_f32_e32 v79, v122, v73
	s_waitcnt lgkmcnt(14)
	v_fma_f32 v68, -v125, v79, v68
	v_fma_f32 v69, v125, v75, v69
	v_fmac_f32_e32 v68, v122, v75
	v_fmac_f32_e32 v69, v122, v79
	v_fma_f32 v70, -v125, v69, v70
	v_fmac_f32_e32 v71, v125, v68
	v_fmac_f32_e32 v70, v122, v68
	v_fmac_f32_e32 v71, v122, v69
	s_waitcnt lgkmcnt(13)
	v_fma_f32 v64, -v125, v71, v64
	v_fma_f32 v65, v125, v70, v65
	v_fmac_f32_e32 v64, v122, v70
	v_fmac_f32_e32 v65, v122, v71
	v_fma_f32 v66, -v125, v65, v66
	v_fmac_f32_e32 v67, v125, v64
	v_fmac_f32_e32 v66, v122, v64
	v_fmac_f32_e32 v67, v122, v65
	s_waitcnt lgkmcnt(12)
	v_fma_f32 v60, -v125, v67, v60
	v_fma_f32 v61, v125, v66, v61
	v_cvt_pk_bf16_f32 v74, v72, v73
	v_cvt_pk_bf16_f32 v72, v75, v79
	v_fmac_f32_e32 v60, v122, v66
	v_fmac_f32_e32 v61, v122, v67
	ds_write2_b32 v166, v74, v72 offset0:88 offset1:156
	v_cvt_pk_bf16_f32 v72, v68, v69
	v_cvt_pk_bf16_f32 v68, v70, v71
	v_fma_f32 v62, -v125, v61, v62
	v_fmac_f32_e32 v63, v125, v60
	ds_write2_b32 v165, v72, v68 offset0:96 offset1:164
	v_cvt_pk_bf16_f32 v68, v64, v65
	v_cvt_pk_bf16_f32 v64, v66, v67
	v_fmac_f32_e32 v62, v122, v60
	v_fmac_f32_e32 v63, v122, v61
	ds_write2_b32 v164, v68, v64 offset0:104 offset1:172
	v_cvt_pk_bf16_f32 v64, v60, v61
	v_cvt_pk_bf16_f32 v60, v62, v63
	ds_write2_b32 v163, v64, v60 offset0:112 offset1:180
	s_waitcnt lgkmcnt(14)
	v_fma_f32 v61, -v125, v63, v56
	v_fma_f32 v60, v125, v62, v57
	v_fmac_f32_e32 v61, v122, v62
	v_fmac_f32_e32 v60, v122, v63
	v_mov_b32_e32 v56, v125
	v_pk_fma_f32 v[56:57], v[56:57], v[60:61], v[58:59] op_sel_hi:[0,1,1] neg_lo:[1,0,0]
	v_mov_b32_e32 v58, v61
	v_mov_b32_e32 v59, v60
	v_pk_fma_f32 v[130:131], v[122:123], v[58:59], v[56:57] op_sel_hi:[0,1,1]
	v_cvt_pk_bf16_f32 v62, v61, v60
	v_cvt_pk_bf16_f32 v56, v130, v131
	ds_write2_b32 v162, v62, v56 offset0:120 offset1:188
	ds_read_b64 v[100:101], v117
	ds_read_b64 v[102:103], v117 offset:528
	ds_read_b64 v[96:97], v117 offset:1056
	ds_read_b64 v[98:99], v117 offset:1584
	ds_read_b64 v[92:93], v161 offset:64
	ds_read_b64 v[94:95], v161 offset:592
	ds_read_b64 v[88:89], v161 offset:1120
	ds_read_b64 v[90:91], v161 offset:1648
	ds_read_b64 v[84:85], v160 offset:128
	ds_read_b64 v[86:87], v160 offset:656
	ds_read_b64 v[80:81], v160 offset:1184
	ds_read_b64 v[82:83], v160 offset:1712
	ds_read_b64 v[76:77], v159 offset:192
	ds_read_b64 v[78:79], v159 offset:720
	ds_read_b64 v[72:73], v159 offset:1248
	ds_read_b64 v[74:75], v159 offset:1776
	s_waitcnt lgkmcnt(0)
	v_mov_b32_e32 v214, v100
	v_mov_b32_e32 v218, v101
	v_mov_b32_e32 v215, v102
	v_mov_b32_e32 v219, v103
	v_mov_b32_e32 v216, v96
	v_mov_b32_e32 v220, v97
	v_mov_b32_e32 v217, v98
	v_mov_b32_e32 v221, v99
	v_mov_b32_e32 v222, v92
	v_mov_b32_e32 v226, v93
	v_mov_b32_e32 v223, v94
	v_mov_b32_e32 v227, v95
	v_mov_b32_e32 v224, v88
	v_mov_b32_e32 v228, v89
	v_mov_b32_e32 v225, v90
	v_mov_b32_e32 v229, v91
	v_mov_b32_e32 v230, v84
	v_mov_b32_e32 v234, v85
	v_mov_b32_e32 v231, v86
	v_mov_b32_e32 v235, v87
	v_mov_b32_e32 v232, v80
	v_mov_b32_e32 v236, v81
	v_mov_b32_e32 v233, v82
	v_mov_b32_e32 v237, v83
	v_mov_b32_e32 v238, v76
	v_mov_b32_e32 v242, v77
	v_mov_b32_e32 v239, v78
	v_mov_b32_e32 v243, v79
	v_mov_b32_e32 v240, v72
	v_mov_b32_e32 v244, v73
	v_mov_b32_e32 v241, v74
	v_mov_b32_e32 v245, v75
.LBB0_417:
	s_waitcnt vmcnt(1)
	s_cmp_lt_u32 s23, 16
	s_cselect_b64 s[26:27], -1, 0
	s_add_i32 s25, s24, 0xfffeff00
	s_and_b64 s[26:27], s[26:27], exec
	s_cselect_b32 s25, s24, s25
	s_cselect_b32 s26, s54, s56
	s_cselect_b32 s27, s55, s57
	s_add_u32 s26, s26, s25
	s_addc_u32 s27, s27, 0
	s_min_i32 s25, s23, 0x10c
	s_cmp_lt_u32 s23, 13
	s_cselect_b64 s[30:31], -1, 0
	s_lshl_b32 s25, s25, 4
	s_and_b64 s[30:31], s[30:31], exec
	s_movk_i32 s30, 0xff30
	s_cselect_b32 s30, 0x10030, s30
	s_cselect_b32 s31, s55, s57
	s_cselect_b32 s34, s54, s56
	s_add_i32 s25, s25, s30
	s_add_u32 s25, s34, s25
	s_addc_u32 s30, s31, 0
	v_cndmask_b32_e64 v170, 0, v53, s[38:39]
	v_cndmask_b32_e64 v171, 0, v52, s[38:39]
	v_mov_b32_e32 v53, s30
	v_or_b32_e32 v52, s25, v104
	v_lshlrev_b64 v[52:53], 11, v[52:53]
	v_lshl_add_u64 v[52:53], v[126:127], 0, v[52:53]
	v_add_u32_e32 v132, v134, v107
	v_cndmask_b32_e64 v133, 0, v55, s[38:39]
	v_cndmask_b32_e64 v148, 0, v54, s[38:39]
	global_load_dwordx4 v[52:55], v[52:53], off
	ds_read_b128 v[56:59], v132 offset:8448
	ds_read_b128 v[60:63], v132 offset:8512
	ds_read_b128 v[64:67], v132 offset:8576
	ds_read_b128 v[68:71], v132 offset:8640
	s_waitcnt lgkmcnt(0)
; #define LAS __attribute__((address_space(3)))
; DI unsigned pk2(float lo, float hi) { f32x2 v = {lo, hi}; bf16x2_t b = __builtin_convertvector(v, bf16x2_t); return __builtin_bit_cast(unsigned, b); }
; #define MFMA16(a, b, c) __builtin_amdgcn_mfma_f32_16x16x32_bf16((a), (b), (c), 0, 0, 0)
; #define S5_CB() asm volatile("" ::: "memory")
; DI void s5_phase(const KArgs& a, int zz, int o, const bf16_t* H, bf16_t* YF, bf16_t* YB, LAS unsigned char* lds, int G, int bid, int wave, int lane) {
;     ...
;         auto iter = [&](const int ci, const bool do_c) __attribute__((always_inline)) {
;             const size_t row0 = chunk_row(ci);
;             const u32x4 u3 = loadu(ci + 3);
;             f32x2 bu[16];
; #pragma unroll
;             for (int s = 0; s < 16; ++s) { const int tt = DIRC ? 15 - s : s; bu[s] = *(const LAS f32x2*)(BU + tt * 132 + 2 * lane); }
;             bf16x8 Ax[4];
;             if (do_c) {
; #pragma unroll
;                 for (int kb = 0; kb < 4; ++kb) Ax[kb] = *(const LAS bf16x8*)(XS + fr * 68 + kb * 16 + fq * 4); }
;             S5_CB();
;             stageA(u1);
;             S5_CB();
; #pragma unroll
;             for (int s = 0; s < 16; ++s) { const int tt = DIRC ? 15 - s : s;
;                 const float nr = __builtin_fmaf(abr, xr, __builtin_fmaf(nabi, xi, bu[s][0])); const float ni = __builtin_fmaf(abr, xi, __builtin_fmaf(abi, xr, bu[s][1])); xr = nr; xi = ni;
;                 XS[tt * 68 + lane] = pk2(xr, xi); }
;             if (do_c) {
;                 f32x4 ya = (f32x4){0.f, 0.f, 0.f, 0.f};
; #pragma unroll
;                 for (int kb = 0; kb < 4; ++kb) ya = MFMA16(Cb[kb], Ax[kb], ya);
;                 u32x2 w; w.x = pk2(ya[0], ya[1]); w.y = pk2(ya[2], ya[3]); *(u32x2*)(Y + (rowprev + fr) * D + g * 16 + fq * 4) = w; }
;             S5_CB();
;             rowprev = row0; u1 = u2; u2 = u3;
;         };
;         iter(0, false);
;         for (int ci = 1; ci < 272; ++ci) iter(ci, true);
	v_mfma_f32_16x16x32_bf16 v[56:59], v[32:35], v[56:59], 0
	v_mfma_f32_16x16x32_bf16 v[56:59], v[36:39], v[60:63], v[56:59]
	v_mfma_f32_16x16x32_bf16 v[56:59], v[40:43], v[64:67], v[56:59]
	v_mfma_f32_16x16x32_bf16 v[56:59], v[44:47], v[68:71], v[56:59]
	v_fma_f32 v60, -v125, v131, v214
	v_fma_f32 v61, v125, v130, v218
	v_fmac_f32_e32 v60, v122, v130
	v_fmac_f32_e32 v61, v122, v131
	v_fma_f32 v63, -v125, v61, v215
	v_fmac_f32_e32 v219, v125, v60
	v_fmac_f32_e32 v63, v122, v60
	v_fmac_f32_e32 v219, v122, v61
	v_cvt_pk_bf16_f32 v62, v60, v61
	v_cvt_pk_bf16_f32 v60, v63, v219
	ds_write2_b32 v169, v62, v60 offset0:64 offset1:132
	v_fma_f32 v60, -v125, v219, v216
	v_fma_f32 v61, v125, v63, v220
	v_fmac_f32_e32 v60, v122, v63
	v_fmac_f32_e32 v61, v122, v219
	v_fma_f32 v63, -v125, v61, v217
	v_fmac_f32_e32 v221, v125, v60
	v_fmac_f32_e32 v63, v122, v60
	v_fmac_f32_e32 v221, v122, v61
	v_cvt_pk_bf16_f32 v62, v60, v61
	v_cvt_pk_bf16_f32 v60, v63, v221
	ds_write2_b32 v168, v62, v60 offset0:72 offset1:140
	v_fma_f32 v60, -v125, v221, v222
	v_fma_f32 v61, v125, v63, v226
	v_fmac_f32_e32 v60, v122, v63
	v_fmac_f32_e32 v61, v122, v221
	v_fma_f32 v63, -v125, v61, v223
	v_fmac_f32_e32 v227, v125, v60
	v_fmac_f32_e32 v63, v122, v60
	v_fmac_f32_e32 v227, v122, v61
	v_cvt_pk_bf16_f32 v62, v60, v61
	v_cvt_pk_bf16_f32 v60, v63, v227
	ds_write2_b32 v167, v62, v60 offset0:80 offset1:148
	v_fma_f32 v60, -v125, v227, v224
	v_fma_f32 v61, v125, v63, v228
	v_fmac_f32_e32 v60, v122, v63
	v_fmac_f32_e32 v61, v122, v227
	v_fma_f32 v63, -v125, v61, v225
	v_fmac_f32_e32 v229, v125, v60
	v_fmac_f32_e32 v63, v122, v60
	v_fmac_f32_e32 v229, v122, v61
	v_cvt_pk_bf16_f32 v62, v60, v61
	v_cvt_pk_bf16_f32 v60, v63, v229
	ds_write2_b32 v166, v62, v60 offset0:88 offset1:156
	v_fma_f32 v60, -v125, v229, v230
	v_fma_f32 v61, v125, v63, v234
	v_fmac_f32_e32 v60, v122, v63
	v_fmac_f32_e32 v61, v122, v229
	v_fma_f32 v63, -v125, v61, v231
	v_fmac_f32_e32 v235, v125, v60
	v_fmac_f32_e32 v63, v122, v60
	v_fmac_f32_e32 v235, v122, v61
	v_cvt_pk_bf16_f32 v62, v60, v61
	v_cvt_pk_bf16_f32 v60, v63, v235
	ds_write2_b32 v165, v62, v60 offset0:96 offset1:164
	v_fma_f32 v60, -v125, v235, v232
	v_fma_f32 v61, v125, v63, v236
	v_fmac_f32_e32 v60, v122, v63
	v_fmac_f32_e32 v61, v122, v235
	v_fma_f32 v63, -v125, v61, v233
	v_fmac_f32_e32 v237, v125, v60
	v_fmac_f32_e32 v63, v122, v60
	v_fmac_f32_e32 v237, v122, v61
	v_cvt_pk_bf16_f32 v62, v60, v61
	v_cvt_pk_bf16_f32 v60, v63, v237
	ds_write2_b32 v164, v62, v60 offset0:104 offset1:172
	v_fma_f32 v60, -v125, v237, v238
	v_fma_f32 v61, v125, v63, v242
	v_fmac_f32_e32 v60, v122, v63
	v_fmac_f32_e32 v61, v122, v237
	v_fma_f32 v63, -v125, v61, v239
	v_fmac_f32_e32 v243, v125, v60
	v_fmac_f32_e32 v63, v122, v60
	v_fmac_f32_e32 v243, v122, v61
	v_cvt_pk_bf16_f32 v62, v60, v61
	v_cvt_pk_bf16_f32 v60, v63, v243
	ds_write2_b32 v163, v62, v60 offset0:112 offset1:180
	v_fma_f32 v60, -v125, v243, v240
	v_fma_f32 v61, v125, v63, v244
	v_fmac_f32_e32 v60, v122, v63
	v_fmac_f32_e32 v61, v122, v243
	v_fma_f32 v63, -v125, v61, v241
	v_fmac_f32_e32 v245, v125, v60
	v_fmac_f32_e32 v63, v122, v60
	v_fmac_f32_e32 v245, v122, v61
	v_cvt_pk_bf16_f32 v62, v60, v61
	v_cvt_pk_bf16_f32 v60, v63, v245
	ds_write2_b32 v162, v62, v60 offset0:120 offset1:188
	v_mov_b32_e32 v130, v63
	v_mov_b32_e32 v131, v245
	v_mfma_f32_16x16x32_bf16 v[214:217], v[48:51], v[178:181], 0
	v_mfma_f32_16x16x32_bf16 v[222:225], v[48:51], v[186:189], 0
	v_mfma_f32_16x16x32_bf16 v[230:233], v[48:51], v[194:197], 0
	v_mfma_f32_16x16x32_bf16 v[238:241], v[48:51], v[202:205], 0
	v_mfma_f32_16x16x32_bf16 v[218:221], v[48:51], v[182:185], 0
	v_mfma_f32_16x16x32_bf16 v[226:229], v[48:51], v[190:193], 0
	v_mfma_f32_16x16x32_bf16 v[234:237], v[48:51], v[198:201], 0
	v_mfma_f32_16x16x32_bf16 v[242:245], v[48:51], v[206:209], 0
	v_cvt_pk_bf16_f32 v56, v56, v57
	v_cvt_pk_bf16_f32 v57, v58, v59
	v_lshl_add_u64 v[62:63], s[0:1], 0, v[104:105]
	v_lshlrev_b64 v[62:63], 11, v[62:63]
	v_lshl_add_u64 v[62:63], v[128:129], 0, v[62:63]
	global_store_dwordx2 v[62:63], v[56:57], off
	v_permlane32_swap_b32_e32 v214, v230
	v_permlane32_swap_b32_e32 v222, v238
	v_permlane32_swap_b32_e32 v215, v231
	v_permlane32_swap_b32_e32 v223, v239
	v_permlane32_swap_b32_e32 v216, v232
	v_permlane32_swap_b32_e32 v224, v240
	v_permlane32_swap_b32_e32 v217, v233
	v_permlane32_swap_b32_e32 v225, v241
	v_permlane16_swap_b32_e32 v214, v222
	v_permlane16_swap_b32_e32 v230, v238
	v_permlane16_swap_b32_e32 v215, v223
	v_permlane16_swap_b32_e32 v231, v239
	v_permlane16_swap_b32_e32 v216, v224
	v_permlane16_swap_b32_e32 v232, v240
	v_permlane16_swap_b32_e32 v217, v225
	v_permlane16_swap_b32_e32 v233, v241
	v_permlane32_swap_b32_e32 v218, v234
	v_permlane32_swap_b32_e32 v226, v242
	v_permlane32_swap_b32_e32 v219, v235
	v_permlane32_swap_b32_e32 v227, v243
	v_permlane32_swap_b32_e32 v220, v236
	v_permlane32_swap_b32_e32 v228, v244
	v_permlane32_swap_b32_e32 v221, v237
	v_permlane32_swap_b32_e32 v229, v245
	v_permlane16_swap_b32_e32 v218, v226
	v_permlane16_swap_b32_e32 v234, v242
	v_permlane16_swap_b32_e32 v219, v227
	v_permlane16_swap_b32_e32 v235, v243
	v_permlane16_swap_b32_e32 v220, v228
	v_permlane16_swap_b32_e32 v236, v244
	v_permlane16_swap_b32_e32 v221, v229
	v_permlane16_swap_b32_e32 v237, v245
	s_mov_b64 s[0:1], s[26:27]
	v_mov_b32_e32 v48, v171
	v_mov_b32_e32 v49, v170
	v_mov_b32_e32 v50, v148
	v_mov_b32_e32 v51, v133
	s_add_i32 s23, s23, 1
	s_add_i32 s24, s24, 16
	s_cmp_lg_u32 s24, 0x11100
	s_cbranch_scc1 .LBB0_417
	s_waitcnt vmcnt(0)
	ds_read_b128 v[0:3], v132 offset:8448
	ds_read_b128 v[4:7], v132 offset:8512
	v_lshlrev_b32_e32 v148, 1, v106
	s_waitcnt lgkmcnt(1)
	v_mfma_f32_16x16x32_bf16 v[0:3], v[32:35], v[0:3], 0
	s_waitcnt lgkmcnt(0)
	v_mfma_f32_16x16x32_bf16 v[0:3], v[36:39], v[4:7], v[0:3]
	ds_read_b128 v[4:7], v132 offset:8576
	s_waitcnt lgkmcnt(0)
	v_mfma_f32_16x16x32_bf16 v[0:3], v[40:43], v[4:7], v[0:3]
	ds_read_b128 v[4:7], v132 offset:8640
	s_waitcnt lgkmcnt(0)
	v_mfma_f32_16x16x32_bf16 v[0:3], v[44:47], v[4:7], v[0:3]
	s_nop 7
	v_cvt_pk_bf16_f32 v0, v0, v1
	v_cvt_pk_bf16_f32 v1, v2, v3
	v_mov_b32_e32 v3, s27
	v_or_b32_e32 v2, s26, v104
	v_lshlrev_b64 v[2:3], 11, v[2:3]
	v_lshl_add_u64 v[2:3], s[4:5], 0, v[2:3]
	v_lshl_add_u64 v[2:3], s[52:53], 1, v[2:3]
	v_lshl_add_u64 v[2:3], v[2:3], 0, v[148:149]
	global_store_dwordx2 v[2:3], v[0:1], off
	s_waitcnt lgkmcnt(0)
	s_branch .LBB0_394

; #define LAS __attribute__((address_space(3)))
; DI void attn_phase(const bf16_t* Qb, const bf16_t* Kb, const bf16_t* VT, bf16_t* MIX, LAS unsigned char* lds, int G, int bid, int tid, int wave, int lane) {
;     ...
;         auto qk = [&](f32x16& s0, f32x16& s1, const int kbuf) __attribute__((always_inline)) {
;             const LAS unsigned char* Kl = lds + kbuf * AT_KB;
;             f32x16 z;
; #pragma unroll
;             for (int r = 0; r < 16; ++r) z[r] = 0.f;
; #pragma unroll
;             for (int d0 = 0; d0 < 6; ++d0) {
;                 const bf16x8 a0 = *(const LAS bf16x8*)(Kl + r32 * 208 + d0 * 32 + hi * 16);
;                 const bf16x8 a1 = *(const LAS bf16x8*)(Kl + (32 + r32) * 208 + d0 * 32 + hi * 16);
;                 if (d0 == 0) { s0 = MFMA32(a0, qf[0], z); s1 = MFMA32(a1, qf[0], z); }
;                 else { s0 = MFMA32(a0, qf[d0], s0); s1 = MFMA32(a1, qf[d0], s1); }
;             }
;         };
;         auto softmax_pack = [&](f32x16& s0, f32x16& s1, bf16x8 (&pa)[4]) __attribute__((always_inline)) {
;             float ps0 = 0.f, ps1 = 0.f;
; #pragma unroll
;             for (int r = 0; r < 16; ++r) { s0[r] = __builtin_amdgcn_exp2f(s0[r]); s1[r] = __builtin_amdgcn_exp2f(s1[r]); ps0 += s0[r]; ps1 += s1[r]; }
;             lsum += ps0 + ps1;
;             u32x4 w;
;             w.x = pk2(s0[0], s0[1]); w.y = pk2(s0[2], s0[3]); w.z = pk2(s0[4], s0[5]); w.w = pk2(s0[6], s0[7]); pa[0] = __builtin_bit_cast(bf16x8, w);
;             w.x = pk2(s0[8], s0[9]); w.y = pk2(s0[10], s0[11]); w.z = pk2(s0[12], s0[13]); w.w = pk2(s0[14], s0[15]); pa[1] = __builtin_bit_cast(bf16x8, w);
;             w.x = pk2(s1[0], s1[1]); w.y = pk2(s1[2], s1[3]); w.z = pk2(s1[4], s1[5]); w.w = pk2(s1[6], s1[7]); pa[2] = __builtin_bit_cast(bf16x8, w);
;             w.x = pk2(s1[8], s1[9]); w.y = pk2(s1[10], s1[11]); w.z = pk2(s1[12], s1[13]); w.w = pk2(s1[14], s1[15]); pa[3] = __builtin_bit_cast(bf16x8, w);
;         };
;         auto pv = [&](const bf16x8 (&pa)[4], const int vbuf) __attribute__((always_inline)) {
;             const LAS unsigned char* Vl = lds + 2 * AT_KB + vbuf * AT_VB;
; #pragma unroll
;             for (int kk = 0; kk < 4; ++kk) {
;                 const LAS unsigned char* vp = Vl + r32 * 144 + kk * 32 + hi * 16;
;                 const bf16x8 b0 = *(const LAS bf16x8*)(vp);
;                 const bf16x8 b1 = *(const LAS bf16x8*)(vp + 32 * 144);
.LBB0_454:
	ds_read_b128 v[64:67], v219 offset:13312
	ds_read_b128 v[132:135], v219 offset:13344
	s_nop 4
	v_exp_f32_e32 v169, v48
	v_exp_f32_e32 v171, v49
	v_exp_f32_e32 v173, v50
	s_waitcnt lgkmcnt(1)
	v_mfma_f32_32x32x16_bf16 v[80:95], v[64:67], v[128:131], 0
	ds_read_b128 v[64:67], v219 offset:19968
	ds_read_b128 v[136:139], v219 offset:20000
	v_exp_f32_e32 v175, v51
	v_exp_f32_e32 v177, v52
	v_exp_f32_e32 v181, v53
	v_exp_f32_e32 v183, v54
	v_exp_f32_e32 v185, v55
	v_cvt_pk_bf16_f32 v48, v169, v171
	s_waitcnt lgkmcnt(1)
	v_mfma_f32_32x32x16_bf16 v[64:79], v[64:67], v[128:131], 0
	v_cvt_pk_bf16_f32 v49, v173, v175
	v_cvt_pk_bf16_f32 v50, v177, v181
	v_cvt_pk_bf16_f32 v51, v183, v185
	v_exp_f32_e32 v179, v56
	v_exp_f32_e32 v191, v57
	v_exp_f32_e32 v189, v58
	v_exp_f32_e32 v187, v59
	v_mfma_f32_32x32x16_bf16 v[80:95], v[132:135], v[124:127], v[80:95]
	v_exp_f32_e32 v195, v60
	v_exp_f32_e32 v193, v61
	v_exp_f32_e32 v221, v62
	v_exp_f32_e32 v197, v63
	v_cvt_pk_bf16_f32 v60, v179, v191
	v_cvt_pk_bf16_f32 v61, v189, v187
	v_cvt_pk_bf16_f32 v62, v195, v193
	s_waitcnt lgkmcnt(0)
	v_mfma_f32_32x32x16_bf16 v[64:79], v[136:139], v[124:127], v[64:79]
	ds_read_b128 v[132:135], v219 offset:13376
	ds_read_b128 v[136:139], v219 offset:13408
	v_cvt_pk_bf16_f32 v63, v221, v197
	v_exp_f32_e32 v229, v32
	v_exp_f32_e32 v227, v33
	v_exp_f32_e32 v225, v34
	v_exp_f32_e32 v223, v35
	v_exp_f32_e32 v230, v36
	s_waitcnt lgkmcnt(1)
	v_mfma_f32_32x32x16_bf16 v[80:95], v[132:135], v[120:123], v[80:95]
	ds_read_b128 v[132:135], v219 offset:20032
	ds_read_b128 v[140:143], v219 offset:20064
	v_exp_f32_e32 v228, v37
	v_exp_f32_e32 v226, v38
	v_exp_f32_e32 v224, v39
	v_cvt_pk_bf16_f32 v32, v229, v227
	v_cvt_pk_bf16_f32 v33, v225, v223
	v_cvt_pk_bf16_f32 v34, v230, v228
	s_waitcnt lgkmcnt(1)
	v_mfma_f32_32x32x16_bf16 v[64:79], v[132:135], v[120:123], v[64:79]
	v_cvt_pk_bf16_f32 v35, v226, v224
	s_add_i32 s20, s38, -1
	s_min_u32 s39, s20, s31
	v_exp_f32_e32 v222, v40
	v_exp_f32_e32 v233, v41
	v_exp_f32_e32 v232, v42
	v_exp_f32_e32 v231, v43
	v_mfma_f32_32x32x16_bf16 v[80:95], v[136:139], v[116:119], v[80:95]
	ds_read_b128 v[132:135], v219 offset:13440
	ds_read_b128 v[136:139], v219 offset:13472
	s_mul_i32 s20, s39, 0x1800
	s_lshl_b64 s[26:27], s[20:21], 1
	s_add_u32 s26, s8, s26
	s_addc_u32 s27, s9, s27
	v_exp_f32_e32 v235, v44
	v_exp_f32_e32 v234, v45
	s_waitcnt lgkmcnt(2)
	v_mfma_f32_32x32x16_bf16 v[64:79], v[140:143], v[116:119], v[64:79]
	v_exp_f32_e32 v237, v46
	v_exp_f32_e32 v236, v47
	v_cvt_pk_bf16_f32 v44, v222, v233
	v_cvt_pk_bf16_f32 v45, v232, v231
	v_cvt_pk_bf16_f32 v46, v235, v234
	v_cvt_pk_bf16_f32 v47, v237, v236
	s_waitcnt lgkmcnt(1)
	v_mfma_f32_32x32x16_bf16 v[80:95], v[132:135], v[108:111], v[80:95]
	ds_read_b128 v[132:135], v219 offset:20096
	ds_read_b128 v[140:143], v219 offset:20128
	ds_read_b128 v[52:55], v220 offset:26624
	ds_read_b128 v[56:59], v220 offset:26656
	ds_read_b128 v[36:39], v220 offset:26688
	ds_read_b128 v[40:43], v220 offset:26720
	s_waitcnt lgkmcnt(3)
	v_mfma_f32_32x32x16_bf16 v[16:31], v[48:51], v[52:55], v[16:31]
	v_add_f32_e32 v241, 0, v169
	v_add_f32_e32 v242, 0, v229
	v_add_f32_e32 v241, v171, v241
	v_add_f32_e32 v242, v227, v242
	ds_read_b128 v[52:55], v220 offset:31232
	v_mfma_f32_32x32x16_bf16 v[64:79], v[132:135], v[108:111], v[64:79]
	ds_read_b128 v[132:135], v220 offset:31264
	s_waitcnt lgkmcnt(1)
	v_mfma_f32_32x32x16_bf16 v[0:15], v[48:51], v[52:55], v[0:15]
	v_add_f32_e32 v241, v173, v241
	v_add_f32_e32 v242, v225, v242
	v_add_f32_e32 v241, v175, v241
	v_add_f32_e32 v242, v223, v242
	ds_read_b128 v[48:51], v220 offset:31328
	v_mfma_f32_32x32x16_bf16 v[16:31], v[60:63], v[56:59], v[16:31]
	v_add_f32_e32 v241, v177, v241
	v_add_f32_e32 v242, v230, v242
	v_add_f32_e32 v241, v181, v241
	v_add_f32_e32 v242, v228, v242
	s_waitcnt lgkmcnt(1)
	v_mfma_f32_32x32x16_bf16 v[0:15], v[60:63], v[132:135], v[0:15]
	v_add_f32_e32 v241, v183, v241
	v_add_f32_e32 v242, v226, v242
	v_add_f32_e32 v241, v185, v241
	v_add_f32_e32 v242, v224, v242
	v_mfma_f32_32x32x16_bf16 v[16:31], v[32:35], v[36:39], v[16:31]
	v_add_f32_e32 v241, v179, v241
	v_add_f32_e32 v242, v222, v242
	v_add_f32_e32 v241, v191, v241
	v_add_f32_e32 v242, v233, v242
	ds_read_b128 v[36:39], v220 offset:31296
	s_waitcnt lgkmcnt(0)
	v_mfma_f32_32x32x16_bf16 v[0:15], v[32:35], v[36:39], v[0:15]
	v_add_f32_e32 v241, v189, v241
	v_add_f32_e32 v242, v232, v242
	v_add_f32_e32 v241, v187, v241
	v_add_f32_e32 v242, v231, v242
	v_lshl_add_u64 v[32:33], v[160:161], 1, s[26:27]
	v_mfma_f32_32x32x16_bf16 v[80:95], v[136:139], v[100:103], v[80:95]
	v_mfma_f32_32x32x16_bf16 v[64:79], v[140:143], v[100:103], v[64:79]
	global_load_dwordx4 v[140:143], v[32:33], off
	global_load_dwordx4 v[136:139], v215, s[26:27]
	global_load_dwordx4 v[132:135], v[200:201], off
	s_waitcnt vmcnt(4)
	ds_write_b128 v216, v[112:115]
	v_mfma_f32_32x32x16_bf16 v[16:31], v[44:47], v[40:43], v[16:31]
	v_add_f32_e32 v241, v195, v241
	v_add_f32_e32 v242, v235, v242
	v_add_f32_e32 v241, v193, v241
	v_add_f32_e32 v242, v234, v242
	v_add_f32_e32 v241, v221, v241
	v_mfma_f32_32x32x16_bf16 v[0:15], v[44:47], v[48:51], v[0:15]
	v_add_f32_e32 v242, v237, v242
	v_add_f32_e32 v241, v197, v241
	v_add_f32_e32 v242, v236, v242
	v_add_f32_e32 v241, v241, v242
	v_add_f32_e32 v167, v167, v241
	s_and_saveexec_b64 s[26:27], s[4:5]
	ds_write_b128 v218, v[104:107]
	s_or_b64 exec, exec, s[26:27]
	s_waitcnt vmcnt(3)
	ds_write_b128 v217, v[96:99] offset:35840
	s_waitcnt lgkmcnt(0)
	s_barrier
; #define LAS __attribute__((address_space(3)))
; DI void attn_phase(const bf16_t* Qb, const bf16_t* Kb, const bf16_t* VT, bf16_t* MIX, LAS unsigned char* lds, int G, int bid, int tid, int wave, int lane) {
;     ...
;         auto qk = [&](f32x16& s0, f32x16& s1, const int kbuf) __attribute__((always_inline)) {
;             const LAS unsigned char* Kl = lds + kbuf * AT_KB;
;             f32x16 z;
; #pragma unroll
;             for (int r = 0; r < 16; ++r) z[r] = 0.f;
; #pragma unroll
;             for (int d0 = 0; d0 < 6; ++d0) {
;                 const bf16x8 a0 = *(const LAS bf16x8*)(Kl + r32 * 208 + d0 * 32 + hi * 16);
;                 const bf16x8 a1 = *(const LAS bf16x8*)(Kl + (32 + r32) * 208 + d0 * 32 + hi * 16);
;                 if (d0 == 0) { s0 = MFMA32(a0, qf[0], z); s1 = MFMA32(a1, qf[0], z); }
;                 else { s0 = MFMA32(a0, qf[d0], s0); s1 = MFMA32(a1, qf[d0], s1); }
;             }
;         };
;         auto softmax_pack = [&](f32x16& s0, f32x16& s1, bf16x8 (&pa)[4]) __attribute__((always_inline)) {
;             float ps0 = 0.f, ps1 = 0.f;
; #pragma unroll
;             for (int r = 0; r < 16; ++r) { s0[r] = __builtin_amdgcn_exp2f(s0[r]); s1[r] = __builtin_amdgcn_exp2f(s1[r]); ps0 += s0[r]; ps1 += s1[r]; }
;             lsum += ps0 + ps1;
;             u32x4 w;
;             w.x = pk2(s0[0], s0[1]); w.y = pk2(s0[2], s0[3]); w.z = pk2(s0[4], s0[5]); w.w = pk2(s0[6], s0[7]); pa[0] = __builtin_bit_cast(bf16x8, w);
;             w.x = pk2(s0[8], s0[9]); w.y = pk2(s0[10], s0[11]); w.z = pk2(s0[12], s0[13]); w.w = pk2(s0[14], s0[15]); pa[1] = __builtin_bit_cast(bf16x8, w);
;             w.x = pk2(s1[0], s1[1]); w.y = pk2(s1[2], s1[3]); w.z = pk2(s1[4], s1[5]); w.w = pk2(s1[6], s1[7]); pa[2] = __builtin_bit_cast(bf16x8, w);
;             w.x = pk2(s1[8], s1[9]); w.y = pk2(s1[10], s1[11]); w.z = pk2(s1[12], s1[13]); w.w = pk2(s1[14], s1[15]); pa[3] = __builtin_bit_cast(bf16x8, w);
;         };
;         auto pv = [&](const bf16x8 (&pa)[4], const int vbuf) __attribute__((always_inline)) {
;             const LAS unsigned char* Vl = lds + 2 * AT_KB + vbuf * AT_VB;
; #pragma unroll
;             for (int kk = 0; kk < 4; ++kk) {
;                 const LAS unsigned char* vp = Vl + r32 * 144 + kk * 32 + hi * 16;
;                 const bf16x8 b0 = *(const LAS bf16x8*)(vp);
;                 const bf16x8 b1 = *(const LAS bf16x8*)(vp + 32 * 144);
	ds_read_b128 v[32:35], v219
	ds_read_b128 v[96:99], v219 offset:32
	v_exp_f32_e32 v80, v80
	v_exp_f32_e32 v81, v81
	v_exp_f32_e32 v82, v82
	s_waitcnt lgkmcnt(1)
	v_mfma_f32_32x32x16_bf16 v[48:63], v[32:35], v[128:131], 0
	ds_read_b128 v[32:35], v219 offset:6656
	v_exp_f32_e32 v83, v83
	v_exp_f32_e32 v84, v84
	v_exp_f32_e32 v85, v85
	v_exp_f32_e32 v86, v86
	v_exp_f32_e32 v87, v87
	v_exp_f32_e32 v239, v88
	s_waitcnt lgkmcnt(1)
	v_mfma_f32_32x32x16_bf16 v[48:63], v[96:99], v[124:127], v[48:63]
	ds_read_b128 v[96:99], v219 offset:6688
	v_exp_f32_e32 v238, v89
	v_exp_f32_e32 v89, v90
	v_exp_f32_e32 v88, v91
	v_exp_f32_e32 v91, v92
	v_exp_f32_e32 v93, v93
	v_exp_f32_e32 v92, v94
	s_waitcnt lgkmcnt(1)
	v_mfma_f32_32x32x16_bf16 v[32:47], v[32:35], v[128:131], 0
	v_exp_f32_e32 v90, v95
	v_cvt_pk_bf16_f32 v202, v239, v238
	v_cvt_pk_bf16_f32 v203, v89, v88
	v_cvt_pk_bf16_f32 v204, v91, v93
	v_cvt_pk_bf16_f32 v205, v92, v90
	v_exp_f32_e32 v95, v64
	v_exp_f32_e32 v94, v65
	s_waitcnt lgkmcnt(0)
	v_mfma_f32_32x32x16_bf16 v[32:47], v[96:99], v[124:127], v[32:47]
	ds_read_b128 v[96:99], v219 offset:64
	v_exp_f32_e32 v66, v66
	v_exp_f32_e32 v240, v67
	v_exp_f32_e32 v68, v68
	v_exp_f32_e32 v67, v69
	v_exp_f32_e32 v65, v70
	v_exp_f32_e32 v64, v71
	s_waitcnt lgkmcnt(0)
	v_mfma_f32_32x32x16_bf16 v[48:63], v[96:99], v[120:123], v[48:63]
	ds_read_b128 v[96:99], v219 offset:6720
	v_exp_f32_e32 v72, v72
	v_exp_f32_e32 v71, v73
	v_exp_f32_e32 v70, v74
	v_exp_f32_e32 v69, v75
	v_exp_f32_e32 v74, v76
	v_exp_f32_e32 v76, v77
	s_waitcnt lgkmcnt(0)
	v_mfma_f32_32x32x16_bf16 v[32:47], v[96:99], v[120:123], v[32:47]
	ds_read_b128 v[96:99], v219 offset:96
	v_exp_f32_e32 v75, v78
	v_exp_f32_e32 v73, v79
	s_min_u32 s20, s38, s31
	s_mulk_i32 s20, 0x3000
	s_add_u32 s26, s8, s20
	s_addc_u32 s27, s9, 0
	s_waitcnt lgkmcnt(0)
	v_mfma_f32_32x32x16_bf16 v[48:63], v[96:99], v[116:119], v[48:63]
	ds_read_b128 v[96:99], v219 offset:6752
	v_lshl_add_u64 v[78:79], v[160:161], 1, s[26:27]
	s_lshl_b32 s20, s39, 7
	v_lshl_add_u64 v[206:207], v[198:199], 0, s[20:21]
	s_waitcnt lgkmcnt(0)
	v_mfma_f32_32x32x16_bf16 v[32:47], v[96:99], v[116:119], v[32:47]
	ds_read_b128 v[96:99], v219 offset:128
	s_waitcnt lgkmcnt(0)
	v_mfma_f32_32x32x16_bf16 v[48:63], v[96:99], v[108:111], v[48:63]
	ds_read_b128 v[96:99], v219 offset:6784
	s_waitcnt lgkmcnt(0)
	v_mfma_f32_32x32x16_bf16 v[32:47], v[96:99], v[108:111], v[32:47]
	ds_read_b128 v[96:99], v219 offset:160
	ds_read_b128 v[104:107], v219 offset:6816
	ds_read_b128 v[112:115], v220 offset:40448
	s_waitcnt lgkmcnt(2)
	v_mfma_f32_32x32x16_bf16 v[48:63], v[96:99], v[100:103], v[48:63]
	v_cvt_pk_bf16_f32 v96, v80, v81
	v_cvt_pk_bf16_f32 v97, v82, v83
	v_cvt_pk_bf16_f32 v98, v84, v85
	v_cvt_pk_bf16_f32 v99, v86, v87
	s_waitcnt lgkmcnt(1)
	v_mfma_f32_32x32x16_bf16 v[32:47], v[104:107], v[100:103], v[32:47]
	ds_read_b128 v[104:107], v220 offset:35840
	s_waitcnt lgkmcnt(0)
	v_mfma_f32_32x32x16_bf16 v[16:31], v[96:99], v[104:107], v[16:31]
	v_add_f32_e32 v241, 0, v80
	v_add_f32_e32 v242, 0, v95
	v_add_f32_e32 v241, v81, v241
	v_add_f32_e32 v242, v94, v242
	ds_read_b128 v[104:107], v220 offset:35872
	v_mfma_f32_32x32x16_bf16 v[0:15], v[96:99], v[112:115], v[0:15]
	v_add_f32_e32 v241, v82, v241
	v_add_f32_e32 v242, v66, v242
	v_add_f32_e32 v241, v83, v241
	v_add_f32_e32 v242, v240, v242
	ds_read_b128 v[96:99], v220 offset:40480
	ds_read_b128 v[112:115], v220 offset:40512
	s_waitcnt lgkmcnt(1)
	v_mfma_f32_32x32x16_bf16 v[0:15], v[202:205], v[96:99], v[0:15]
	v_add_f32_e32 v241, v84, v241
	v_add_f32_e32 v242, v68, v242
	v_add_f32_e32 v241, v85, v241
	v_add_f32_e32 v242, v67, v242
	ds_read_b128 v[96:99], v220 offset:35904
	v_mfma_f32_32x32x16_bf16 v[16:31], v[202:205], v[104:107], v[16:31]
	v_add_f32_e32 v241, v86, v241
	v_add_f32_e32 v242, v65, v242
	v_add_f32_e32 v241, v87, v241
	v_add_f32_e32 v242, v64, v242
	v_cvt_pk_bf16_f32 v104, v95, v94
	v_cvt_pk_bf16_f32 v105, v66, v240
	v_cvt_pk_bf16_f32 v106, v68, v67
	v_cvt_pk_bf16_f32 v107, v65, v64
	v_cvt_pk_bf16_f32 v202, v72, v71
	v_cvt_pk_bf16_f32 v203, v70, v69
	v_cvt_pk_bf16_f32 v204, v74, v76
	s_waitcnt lgkmcnt(0)
	v_mfma_f32_32x32x16_bf16 v[16:31], v[104:107], v[96:99], v[16:31]
	v_add_f32_e32 v241, v239, v241
	v_add_f32_e32 v242, v72, v242
	v_add_f32_e32 v241, v238, v241
	v_add_f32_e32 v242, v71, v242
	ds_read_b128 v[96:99], v220 offset:35936
	v_cvt_pk_bf16_f32 v205, v75, v73
	v_mfma_f32_32x32x16_bf16 v[0:15], v[104:107], v[112:115], v[0:15]
	v_add_f32_e32 v241, v89, v241
	v_add_f32_e32 v242, v70, v242
	v_add_f32_e32 v241, v88, v241
	v_add_f32_e32 v242, v69, v242
	global_load_dwordx4 v[104:107], v215, s[26:27]
	s_waitcnt lgkmcnt(0)
	v_mfma_f32_32x32x16_bf16 v[16:31], v[202:205], v[96:99], v[16:31]
	v_add_f32_e32 v241, v91, v241
	v_add_f32_e32 v242, v74, v242
	v_add_f32_e32 v241, v93, v241
	v_add_f32_e32 v242, v76, v242
	v_add_f32_e32 v241, v92, v241
	global_load_dwordx4 v[112:115], v[78:79], off
	global_load_dwordx4 v[96:99], v[206:207], off
	ds_read_b128 v[206:209], v220 offset:40544
	s_waitcnt vmcnt(5)
	ds_write_b128 v216, v[140:143] offset:13312
	s_waitcnt lgkmcnt(1)
	v_mfma_f32_32x32x16_bf16 v[0:15], v[202:205], v[206:209], v[0:15]
	v_add_f32_e32 v242, v75, v242
	v_add_f32_e32 v241, v90, v241
	v_add_f32_e32 v242, v73, v242
	v_add_f32_e32 v241, v241, v242
	v_add_f32_e32 v167, v167, v241
	s_and_saveexec_b64 s[26:27], s[4:5]
	s_cbranch_execz .LBB0_458
	s_waitcnt vmcnt(4)
	ds_write_b128 v218, v[136:139] offset:13312
.LBB0_458:
	s_or_b64 exec, exec, s[26:27]
	s_add_i32 s20, s38, 2
	s_cmp_lt_u32 s38, s30
	v_lshl_add_u64 v[200:201], v[200:201], 0, s[72:73]
	s_waitcnt vmcnt(3)
	ds_write_b128 v217, v[132:135] offset:26624
	s_waitcnt lgkmcnt(0)
	s_barrier
	s_cbranch_scc0 .LBB0_460
	s_mov_b32 s38, s20
	s_branch .LBB0_454
